# P0 x->bf16+sumsq row loop software-pipelined (next 4 rows in flight while current 4 are reduced with DPP adds and stored)
# speedup vs baseline: 1.0086x; 1.0068x over previous
; __global__ void __launch_bounds__(512, 2) hybrid_fwd(Args args) {
;     ...
;         if (sub & 2) for (int m = gw; m < MTOK; m += 4 * NGW) {
;             f32x4 v[4][4];
; #pragma unroll
;             for (int q = 0; q < 4; ++q) { const f32x4* xr = (const f32x4*)xrow(F, m + q * NGW) + F.lane;
; #pragma unroll
;                 for (int j = 0; j < 4; ++j) v[q][j] = xr[64 * j]; }
; #pragma unroll
;             for (int q = 0; q < 4; ++q) { float s = 0.f;
; #pragma unroll
;                 for (int j = 0; j < 4; ++j) s += (v[q][j].x * v[q][j].x + v[q][j].y * v[q][j].y) + (v[q][j].z * v[q][j].z + v[q][j].w * v[q][j].w);
;                 s = wave_sum(s); if (F.lane == 0) SS0[m + q * NGW] = s;
.LBB0_147:
	s_cmpk_gt_i32 s86, 0x7fff
	s_cbranch_scc1 .LBB0_158
	v_mbcnt_lo_u32_b32 v0, -1, 0
	v_mbcnt_hi_u32_b32 v0, -1, v0
	v_and_b32_e32 v1, 64, v0
	v_add_u32_e32 v1, 64, v1
	v_xor_b32_e32 v2, 1, v0
	v_cmp_lt_i32_e32 vcc, v2, v1
	v_mov_b32_e32 v65, 0
	v_lshlrev_b32_e32 v64, 3, v148
	v_cndmask_b32_e32 v2, v0, v2, vcc
	v_lshlrev_b32_e32 v68, 2, v2
	v_xor_b32_e32 v2, 2, v0
	v_cmp_lt_i32_e32 vcc, v2, v1
	v_lshl_add_u64 v[66:67], s[92:93], 0, v[64:65]
	s_lshl_b32 s14, s89, 4
	v_cndmask_b32_e32 v2, v0, v2, vcc
	v_lshlrev_b32_e32 v69, 2, v2
	v_xor_b32_e32 v2, 4, v0
	v_cmp_lt_i32_e32 vcc, v2, v1
	s_mul_i32 s15, s89, 24
	v_lshlrev_b32_e32 v64, 4, v148
	v_cndmask_b32_e32 v2, v0, v2, vcc
	v_lshlrev_b32_e32 v70, 2, v2
	v_xor_b32_e32 v2, 8, v0
	v_cmp_lt_i32_e32 vcc, v2, v1
	s_mov_b32 s6, s86
	s_nop 0
	v_cndmask_b32_e32 v2, v0, v2, vcc
	v_lshlrev_b32_e32 v71, 2, v2
	v_xor_b32_e32 v2, 16, v0
	v_cmp_lt_i32_e32 vcc, v2, v1
	s_nop 1
	v_cndmask_b32_e32 v2, v0, v2, vcc
	v_lshlrev_b32_e32 v72, 2, v2
	v_xor_b32_e32 v2, 32, v0
	v_cmp_lt_i32_e32 vcc, v2, v1
	s_nop 1
	v_cndmask_b32_e32 v0, v0, v2, vcc
	v_lshlrev_b32_e32 v73, 2, v0
	v_cmp_eq_u32_e32 vcc, 63, v148
	s_lshl_b32 s14, s88, 2
	s_mov_b32 s2, s6
	s_add_i32 s0, s2, 0xffffc000
	s_ashr_i32 s3, s2, 31
	s_cmpk_lt_i32 s2, 0x4000
	s_cselect_b32 s1, s3, 0
	s_cselect_b32 s0, s2, s0
	s_cselect_b32 s4, s65, s67
	s_cselect_b32 s5, s64, s66
	s_lshl_b64 s[0:1], s[0:1], 12
	s_add_u32 s0, s5, s0
	s_addc_u32 s1, s4, s1
	global_load_dwordx4 v[0:3], v64, s[0:1]
	global_load_dwordx4 v[4:7], v64, s[0:1] offset:1024
	global_load_dwordx4 v[8:11], v64, s[0:1] offset:2048
	global_load_dwordx4 v[12:15], v64, s[0:1] offset:3072
	s_add_i32 s2, s2, s88
	s_add_i32 s0, s2, 0xffffc000
	s_ashr_i32 s3, s2, 31
	s_cmpk_lt_i32 s2, 0x4000
	s_cselect_b32 s1, s3, 0
	s_cselect_b32 s0, s2, s0
	s_cselect_b32 s4, s65, s67
	s_cselect_b32 s5, s64, s66
	s_lshl_b64 s[0:1], s[0:1], 12
	s_add_u32 s0, s5, s0
	s_addc_u32 s1, s4, s1
	global_load_dwordx4 v[16:19], v64, s[0:1]
	global_load_dwordx4 v[20:23], v64, s[0:1] offset:1024
	global_load_dwordx4 v[24:27], v64, s[0:1] offset:2048
	global_load_dwordx4 v[28:31], v64, s[0:1] offset:3072
	s_add_i32 s2, s2, s88
	s_add_i32 s0, s2, 0xffffc000
	s_ashr_i32 s3, s2, 31
	s_cmpk_lt_i32 s2, 0x4000
	s_cselect_b32 s1, s3, 0
	s_cselect_b32 s0, s2, s0
	s_cselect_b32 s4, s65, s67
	s_cselect_b32 s5, s64, s66
	s_lshl_b64 s[0:1], s[0:1], 12
	s_add_u32 s0, s5, s0
	s_addc_u32 s1, s4, s1
	global_load_dwordx4 v[32:35], v64, s[0:1]
	global_load_dwordx4 v[36:39], v64, s[0:1] offset:1024
	global_load_dwordx4 v[40:43], v64, s[0:1] offset:2048
	global_load_dwordx4 v[44:47], v64, s[0:1] offset:3072
	s_add_i32 s2, s2, s88
	s_add_i32 s0, s2, 0xffffc000
	s_ashr_i32 s3, s2, 31
	s_cmpk_lt_i32 s2, 0x4000
	s_cselect_b32 s1, s3, 0
	s_cselect_b32 s0, s2, s0
	s_cselect_b32 s4, s65, s67
	s_cselect_b32 s5, s64, s66
	s_lshl_b64 s[0:1], s[0:1], 12
	s_add_u32 s0, s5, s0
	s_addc_u32 s1, s4, s1
	global_load_dwordx4 v[48:51], v64, s[0:1]
	global_load_dwordx4 v[52:55], v64, s[0:1] offset:1024
	global_load_dwordx4 v[56:59], v64, s[0:1] offset:2048
	global_load_dwordx4 v[60:63], v64, s[0:1] offset:3072
	s_add_i32 s7, s6, s14
	s_cmpk_gt_i32 s7, 0x7fff
	s_cbranch_scc1 .Lp0b_only
	s_mov_b32 s2, s7
	s_add_i32 s0, s2, 0xffffc000
	s_ashr_i32 s3, s2, 31
	s_cmpk_lt_i32 s2, 0x4000
	s_cselect_b32 s1, s3, 0
	s_cselect_b32 s0, s2, s0
	s_cselect_b32 s4, s65, s67
	s_cselect_b32 s5, s64, s66
	s_lshl_b64 s[0:1], s[0:1], 12
	s_add_u32 s0, s5, s0
	s_addc_u32 s1, s4, s1
	global_load_dwordx4 v[76:79], v64, s[0:1]
	global_load_dwordx4 v[80:83], v64, s[0:1] offset:1024
	global_load_dwordx4 v[84:87], v64, s[0:1] offset:2048
	global_load_dwordx4 v[88:91], v64, s[0:1] offset:3072
	s_add_i32 s2, s2, s88
	s_add_i32 s0, s2, 0xffffc000
	s_ashr_i32 s3, s2, 31
	s_cmpk_lt_i32 s2, 0x4000
	s_cselect_b32 s1, s3, 0
	s_cselect_b32 s0, s2, s0
	s_cselect_b32 s4, s65, s67
	s_cselect_b32 s5, s64, s66
	s_lshl_b64 s[0:1], s[0:1], 12
	s_add_u32 s0, s5, s0
	s_addc_u32 s1, s4, s1
	global_load_dwordx4 v[92:95], v64, s[0:1]
	global_load_dwordx4 v[96:99], v64, s[0:1] offset:1024
	global_load_dwordx4 v[100:103], v64, s[0:1] offset:2048
	global_load_dwordx4 v[104:107], v64, s[0:1] offset:3072
	s_add_i32 s2, s2, s88
	s_add_i32 s0, s2, 0xffffc000
	s_ashr_i32 s3, s2, 31
	s_cmpk_lt_i32 s2, 0x4000
	s_cselect_b32 s1, s3, 0
	s_cselect_b32 s0, s2, s0
	s_cselect_b32 s4, s65, s67
	s_cselect_b32 s5, s64, s66
	s_lshl_b64 s[0:1], s[0:1], 12
	s_add_u32 s0, s5, s0
	s_addc_u32 s1, s4, s1
	global_load_dwordx4 v[108:111], v64, s[0:1]
	global_load_dwordx4 v[112:115], v64, s[0:1] offset:1024
	global_load_dwordx4 v[116:119], v64, s[0:1] offset:2048
	global_load_dwordx4 v[120:123], v64, s[0:1] offset:3072
	s_add_i32 s2, s2, s88
	s_add_i32 s0, s2, 0xffffc000
	s_ashr_i32 s3, s2, 31
	s_cmpk_lt_i32 s2, 0x4000
	s_cselect_b32 s1, s3, 0
	s_cselect_b32 s0, s2, s0
	s_cselect_b32 s4, s65, s67
	s_cselect_b32 s5, s64, s66
	s_lshl_b64 s[0:1], s[0:1], 12
	s_add_u32 s0, s5, s0
	s_addc_u32 s1, s4, s1
	global_load_dwordx4 v[124:127], v64, s[0:1]
	global_load_dwordx4 v[128:131], v64, s[0:1] offset:1024
	global_load_dwordx4 v[132:135], v64, s[0:1] offset:2048
	global_load_dwordx4 v[136:139], v64, s[0:1] offset:3072
	s_waitcnt vmcnt(28)
	v_mul_f32_e32 v68, v1, v1
	v_mul_f32_e32 v73, v3, v3
	v_fmac_f32_e32 v68, v0, v0
	v_fmac_f32_e32 v73, v2, v2
	v_add_f32_e32 v68, v68, v73
	v_mul_f32_e32 v72, v5, v5
	v_mul_f32_e32 v73, v7, v7
	v_fmac_f32_e32 v72, v4, v4
	v_fmac_f32_e32 v73, v6, v6
	v_add_f32_e32 v72, v72, v73
	v_add_f32_e32 v68, v68, v72
	v_mul_f32_e32 v72, v9, v9
	v_mul_f32_e32 v73, v11, v11
	v_fmac_f32_e32 v72, v8, v8
	v_fmac_f32_e32 v73, v10, v10
	v_add_f32_e32 v72, v72, v73
	v_add_f32_e32 v68, v68, v72
	v_mul_f32_e32 v72, v13, v13
	v_mul_f32_e32 v73, v15, v15
	v_fmac_f32_e32 v72, v12, v12
	v_fmac_f32_e32 v73, v14, v14
	v_add_f32_e32 v72, v72, v73
	v_add_f32_e32 v68, v68, v72
	s_waitcnt vmcnt(24)
; DI unsigned pk2(float lo, float hi) { f32x2_t v = {lo, hi}; bf16x2_t b = __builtin_convertvector(v, bf16x2_t); return __builtin_bit_cast(unsigned, b); }
; __global__ void __launch_bounds__(512, 2) hybrid_fwd(Args args) {
;     ...
;             for (int q = 0; q < 4; ++q) { float s = 0.f;
; #pragma unroll
;                 for (int j = 0; j < 4; ++j) s += (v[q][j].x * v[q][j].x + v[q][j].y * v[q][j].y) + (v[q][j].z * v[q][j].z + v[q][j].w * v[q][j].w);
;                 s = wave_sum(s); if (F.lane == 0) SS0[m + q * NGW] = s;
;                 u32x2* o8 = (u32x2*)(XB + (size_t)(m + q * NGW) * DM) + F.lane;
; #pragma unroll
;                 for (int j = 0; j < 4; ++j) { u32x2 w; w.x = pk2(v[q][j].x, v[q][j].y); w.y = pk2(v[q][j].z, v[q][j].w); o8[64 * j] = w; } }
	v_mul_f32_e32 v69, v17, v17
	v_mul_f32_e32 v73, v19, v19
	v_fmac_f32_e32 v69, v16, v16
	v_fmac_f32_e32 v73, v18, v18
	v_add_f32_e32 v69, v69, v73
	v_mul_f32_e32 v72, v21, v21
	v_mul_f32_e32 v73, v23, v23
	v_fmac_f32_e32 v72, v20, v20
	v_fmac_f32_e32 v73, v22, v22
	v_add_f32_e32 v72, v72, v73
	v_add_f32_e32 v69, v69, v72
	v_mul_f32_e32 v72, v25, v25
	v_mul_f32_e32 v73, v27, v27
	v_fmac_f32_e32 v72, v24, v24
	v_fmac_f32_e32 v73, v26, v26
	v_add_f32_e32 v72, v72, v73
	v_add_f32_e32 v69, v69, v72
	v_mul_f32_e32 v72, v29, v29
	v_mul_f32_e32 v73, v31, v31
	v_fmac_f32_e32 v72, v28, v28
	v_fmac_f32_e32 v73, v30, v30
	v_add_f32_e32 v72, v72, v73
	v_add_f32_e32 v69, v69, v72
	s_waitcnt vmcnt(20)
	v_mul_f32_e32 v70, v33, v33
	v_mul_f32_e32 v73, v35, v35
	v_fmac_f32_e32 v70, v32, v32
	v_fmac_f32_e32 v73, v34, v34
	v_add_f32_e32 v70, v70, v73
	v_mul_f32_e32 v72, v37, v37
	v_mul_f32_e32 v73, v39, v39
	v_fmac_f32_e32 v72, v36, v36
	v_fmac_f32_e32 v73, v38, v38
	v_add_f32_e32 v72, v72, v73
	v_add_f32_e32 v70, v70, v72
	v_mul_f32_e32 v72, v41, v41
	v_mul_f32_e32 v73, v43, v43
	v_fmac_f32_e32 v72, v40, v40
	v_fmac_f32_e32 v73, v42, v42
	v_add_f32_e32 v72, v72, v73
	v_add_f32_e32 v70, v70, v72
	v_mul_f32_e32 v72, v45, v45
	v_mul_f32_e32 v73, v47, v47
	v_fmac_f32_e32 v72, v44, v44
	v_fmac_f32_e32 v73, v46, v46
	v_add_f32_e32 v72, v72, v73
	v_add_f32_e32 v70, v70, v72
	s_waitcnt vmcnt(16)
	v_mul_f32_e32 v71, v49, v49
	v_mul_f32_e32 v73, v51, v51
	v_fmac_f32_e32 v71, v48, v48
	v_fmac_f32_e32 v73, v50, v50
	v_add_f32_e32 v71, v71, v73
	v_mul_f32_e32 v72, v53, v53
	v_mul_f32_e32 v73, v55, v55
	v_fmac_f32_e32 v72, v52, v52
	v_fmac_f32_e32 v73, v54, v54
	v_add_f32_e32 v72, v72, v73
	v_add_f32_e32 v71, v71, v72
	v_mul_f32_e32 v72, v57, v57
	v_mul_f32_e32 v73, v59, v59
	v_fmac_f32_e32 v72, v56, v56
	v_fmac_f32_e32 v73, v58, v58
	v_add_f32_e32 v72, v72, v73
	v_add_f32_e32 v71, v71, v72
	v_mul_f32_e32 v72, v61, v61
	v_mul_f32_e32 v73, v63, v63
	v_fmac_f32_e32 v72, v60, v60
	v_fmac_f32_e32 v73, v62, v62
	v_add_f32_e32 v72, v72, v73
	v_add_f32_e32 v71, v71, v72
	v_add_f32_dpp v68, v68, v68 quad_perm:[1,0,3,2] row_mask:0xf bank_mask:0xf
	v_add_f32_dpp v69, v69, v69 quad_perm:[1,0,3,2] row_mask:0xf bank_mask:0xf
	v_add_f32_dpp v70, v70, v70 quad_perm:[1,0,3,2] row_mask:0xf bank_mask:0xf
	v_add_f32_dpp v71, v71, v71 quad_perm:[1,0,3,2] row_mask:0xf bank_mask:0xf
	v_add_f32_dpp v68, v68, v68 quad_perm:[2,3,0,1] row_mask:0xf bank_mask:0xf
	v_add_f32_dpp v69, v69, v69 quad_perm:[2,3,0,1] row_mask:0xf bank_mask:0xf
	v_add_f32_dpp v70, v70, v70 quad_perm:[2,3,0,1] row_mask:0xf bank_mask:0xf
	v_add_f32_dpp v71, v71, v71 quad_perm:[2,3,0,1] row_mask:0xf bank_mask:0xf
	v_add_f32_dpp v68, v68, v68 row_half_mirror row_mask:0xf bank_mask:0xf
	v_add_f32_dpp v69, v69, v69 row_half_mirror row_mask:0xf bank_mask:0xf
	v_add_f32_dpp v70, v70, v70 row_half_mirror row_mask:0xf bank_mask:0xf
	v_add_f32_dpp v71, v71, v71 row_half_mirror row_mask:0xf bank_mask:0xf
	v_add_f32_dpp v68, v68, v68 row_mirror row_mask:0xf bank_mask:0xf
	v_add_f32_dpp v69, v69, v69 row_mirror row_mask:0xf bank_mask:0xf
	v_add_f32_dpp v70, v70, v70 row_mirror row_mask:0xf bank_mask:0xf
	v_add_f32_dpp v71, v71, v71 row_mirror row_mask:0xf bank_mask:0xf
	v_add_f32_dpp v68, v68, v68 row_bcast:15 row_mask:0xa bank_mask:0xf
	v_add_f32_dpp v69, v69, v69 row_bcast:15 row_mask:0xa bank_mask:0xf
	v_add_f32_dpp v70, v70, v70 row_bcast:15 row_mask:0xa bank_mask:0xf
	v_add_f32_dpp v71, v71, v71 row_bcast:15 row_mask:0xa bank_mask:0xf
	v_add_f32_dpp v68, v68, v68 row_bcast:31 row_mask:0xc bank_mask:0xf
	v_add_f32_dpp v69, v69, v69 row_bcast:31 row_mask:0xc bank_mask:0xf
	v_add_f32_dpp v70, v70, v70 row_bcast:31 row_mask:0xc bank_mask:0xf
	v_add_f32_dpp v71, v71, v71 row_bcast:31 row_mask:0xc bank_mask:0xf
	s_and_saveexec_b64 s[8:9], vcc
	s_mov_b32 s2, s6
	s_ashr_i32 s3, s2, 31
	s_lshl_b64 s[38:39], s[2:3], 2
	s_add_u32 s38, s82, s38
	s_addc_u32 s39, s83, s39
	global_store_dword v65, v68, s[38:39]
	s_add_i32 s2, s2, s88
	s_ashr_i32 s3, s2, 31
	s_lshl_b64 s[38:39], s[2:3], 2
	s_add_u32 s38, s82, s38
	s_addc_u32 s39, s83, s39
	global_store_dword v65, v69, s[38:39]
	s_add_i32 s2, s2, s88
	s_ashr_i32 s3, s2, 31
	s_lshl_b64 s[38:39], s[2:3], 2
	s_add_u32 s38, s82, s38
	s_addc_u32 s39, s83, s39
	global_store_dword v65, v70, s[38:39]
	s_add_i32 s2, s2, s88
	s_ashr_i32 s3, s2, 31
	s_lshl_b64 s[38:39], s[2:3], 2
	s_add_u32 s38, s82, s38
	s_addc_u32 s39, s83, s39
	global_store_dword v65, v71, s[38:39]
	s_or_b64 exec, exec, s[8:9]
	s_mov_b32 s2, s6
	s_ashr_i32 s3, s2, 31
	s_lshl_b64 s[0:1], s[2:3], 11
	v_lshl_add_u64 v[72:73], v[66:67], 0, s[0:1]
	v_cvt_pk_bf16_f32 v0, v0, v1
	v_cvt_pk_bf16_f32 v1, v2, v3
	v_cvt_pk_bf16_f32 v4, v4, v5
	v_cvt_pk_bf16_f32 v5, v6, v7
	v_cvt_pk_bf16_f32 v8, v8, v9
	v_cvt_pk_bf16_f32 v9, v10, v11
	v_cvt_pk_bf16_f32 v12, v12, v13
	v_cvt_pk_bf16_f32 v13, v14, v15
	global_store_dwordx2 v[72:73], v[0:1], off
	global_store_dwordx2 v[72:73], v[4:5], off offset:512
	global_store_dwordx2 v[72:73], v[8:9], off offset:1024
	global_store_dwordx2 v[72:73], v[12:13], off offset:1536
	s_add_i32 s2, s2, s88
	s_ashr_i32 s3, s2, 31
	s_lshl_b64 s[0:1], s[2:3], 11
	v_lshl_add_u64 v[72:73], v[66:67], 0, s[0:1]
	v_cvt_pk_bf16_f32 v16, v16, v17
	v_cvt_pk_bf16_f32 v17, v18, v19
	v_cvt_pk_bf16_f32 v20, v20, v21
	v_cvt_pk_bf16_f32 v21, v22, v23
	v_cvt_pk_bf16_f32 v24, v24, v25
	v_cvt_pk_bf16_f32 v25, v26, v27
	v_cvt_pk_bf16_f32 v28, v28, v29
	v_cvt_pk_bf16_f32 v29, v30, v31
	global_store_dwordx2 v[72:73], v[16:17], off
	global_store_dwordx2 v[72:73], v[20:21], off offset:512
	global_store_dwordx2 v[72:73], v[24:25], off offset:1024
	global_store_dwordx2 v[72:73], v[28:29], off offset:1536
	s_add_i32 s2, s2, s88
	s_ashr_i32 s3, s2, 31
	s_lshl_b64 s[0:1], s[2:3], 11
	v_lshl_add_u64 v[72:73], v[66:67], 0, s[0:1]
	v_cvt_pk_bf16_f32 v32, v32, v33
	v_cvt_pk_bf16_f32 v33, v34, v35
	v_cvt_pk_bf16_f32 v36, v36, v37
	v_cvt_pk_bf16_f32 v37, v38, v39
	v_cvt_pk_bf16_f32 v40, v40, v41
	v_cvt_pk_bf16_f32 v41, v42, v43
	v_cvt_pk_bf16_f32 v44, v44, v45
	v_cvt_pk_bf16_f32 v45, v46, v47
	global_store_dwordx2 v[72:73], v[32:33], off
	global_store_dwordx2 v[72:73], v[36:37], off offset:512
	global_store_dwordx2 v[72:73], v[40:41], off offset:1024
	global_store_dwordx2 v[72:73], v[44:45], off offset:1536
	s_add_i32 s2, s2, s88
	s_ashr_i32 s3, s2, 31
	s_lshl_b64 s[0:1], s[2:3], 11
	v_lshl_add_u64 v[72:73], v[66:67], 0, s[0:1]
	v_cvt_pk_bf16_f32 v48, v48, v49
	v_cvt_pk_bf16_f32 v49, v50, v51
	v_cvt_pk_bf16_f32 v52, v52, v53
	v_cvt_pk_bf16_f32 v53, v54, v55
	v_cvt_pk_bf16_f32 v56, v56, v57
	v_cvt_pk_bf16_f32 v57, v58, v59
	v_cvt_pk_bf16_f32 v60, v60, v61
	v_cvt_pk_bf16_f32 v61, v62, v63
	global_store_dwordx2 v[72:73], v[48:49], off
	global_store_dwordx2 v[72:73], v[52:53], off offset:512
	global_store_dwordx2 v[72:73], v[56:57], off offset:1024
	global_store_dwordx2 v[72:73], v[60:61], off offset:1536
; __global__ void __launch_bounds__(512, 2) hybrid_fwd(Args args) {
;     ...
;         if (sub & 2) for (int m = gw; m < MTOK; m += 4 * NGW) {
;             f32x4 v[4][4];
; #pragma unroll
;             for (int q = 0; q < 4; ++q) { const f32x4* xr = (const f32x4*)xrow(F, m + q * NGW) + F.lane;
; #pragma unroll
;                 for (int j = 0; j < 4; ++j) v[q][j] = xr[64 * j]; }
; #pragma unroll
;             for (int q = 0; q < 4; ++q) { float s = 0.f;
; #pragma unroll
;                 for (int j = 0; j < 4; ++j) s += (v[q][j].x * v[q][j].x + v[q][j].y * v[q][j].y) + (v[q][j].z * v[q][j].z + v[q][j].w * v[q][j].w);
;                 s = wave_sum(s); if (F.lane == 0) SS0[m + q * NGW] = s;
.Lp0b_loop:
	s_add_i32 s6, s7, s14
	s_cmpk_gt_i32 s6, 0x7fff
	s_cbranch_scc1 .Lp0b_lastB
	s_mov_b32 s2, s6
	s_add_i32 s0, s2, 0xffffc000
	s_ashr_i32 s3, s2, 31
	s_cmpk_lt_i32 s2, 0x4000
	s_cselect_b32 s1, s3, 0
	s_cselect_b32 s0, s2, s0
	s_cselect_b32 s4, s65, s67
	s_cselect_b32 s5, s64, s66
	s_lshl_b64 s[0:1], s[0:1], 12
	s_add_u32 s0, s5, s0
	s_addc_u32 s1, s4, s1
	global_load_dwordx4 v[0:3], v64, s[0:1]
	global_load_dwordx4 v[4:7], v64, s[0:1] offset:1024
	global_load_dwordx4 v[8:11], v64, s[0:1] offset:2048
	global_load_dwordx4 v[12:15], v64, s[0:1] offset:3072
	s_add_i32 s2, s2, s88
	s_add_i32 s0, s2, 0xffffc000
	s_ashr_i32 s3, s2, 31
	s_cmpk_lt_i32 s2, 0x4000
	s_cselect_b32 s1, s3, 0
	s_cselect_b32 s0, s2, s0
	s_cselect_b32 s4, s65, s67
	s_cselect_b32 s5, s64, s66
	s_lshl_b64 s[0:1], s[0:1], 12
	s_add_u32 s0, s5, s0
	s_addc_u32 s1, s4, s1
	global_load_dwordx4 v[16:19], v64, s[0:1]
	global_load_dwordx4 v[20:23], v64, s[0:1] offset:1024
	global_load_dwordx4 v[24:27], v64, s[0:1] offset:2048
	global_load_dwordx4 v[28:31], v64, s[0:1] offset:3072
	s_add_i32 s2, s2, s88
	s_add_i32 s0, s2, 0xffffc000
	s_ashr_i32 s3, s2, 31
	s_cmpk_lt_i32 s2, 0x4000
	s_cselect_b32 s1, s3, 0
	s_cselect_b32 s0, s2, s0
	s_cselect_b32 s4, s65, s67
	s_cselect_b32 s5, s64, s66
	s_lshl_b64 s[0:1], s[0:1], 12
	s_add_u32 s0, s5, s0
	s_addc_u32 s1, s4, s1
	global_load_dwordx4 v[32:35], v64, s[0:1]
	global_load_dwordx4 v[36:39], v64, s[0:1] offset:1024
	global_load_dwordx4 v[40:43], v64, s[0:1] offset:2048
	global_load_dwordx4 v[44:47], v64, s[0:1] offset:3072
	s_add_i32 s2, s2, s88
	s_add_i32 s0, s2, 0xffffc000
	s_ashr_i32 s3, s2, 31
	s_cmpk_lt_i32 s2, 0x4000
	s_cselect_b32 s1, s3, 0
	s_cselect_b32 s0, s2, s0
	s_cselect_b32 s4, s65, s67
	s_cselect_b32 s5, s64, s66
	s_lshl_b64 s[0:1], s[0:1], 12
	s_add_u32 s0, s5, s0
	s_addc_u32 s1, s4, s1
	global_load_dwordx4 v[48:51], v64, s[0:1]
	global_load_dwordx4 v[52:55], v64, s[0:1] offset:1024
	global_load_dwordx4 v[56:59], v64, s[0:1] offset:2048
	global_load_dwordx4 v[60:63], v64, s[0:1] offset:3072
	s_waitcnt vmcnt(48)
	v_mul_f32_e32 v68, v77, v77
	v_mul_f32_e32 v73, v79, v79
	v_fmac_f32_e32 v68, v76, v76
	v_fmac_f32_e32 v73, v78, v78
	v_add_f32_e32 v68, v68, v73
	v_mul_f32_e32 v72, v81, v81
	v_mul_f32_e32 v73, v83, v83
	v_fmac_f32_e32 v72, v80, v80
	v_fmac_f32_e32 v73, v82, v82
	v_add_f32_e32 v72, v72, v73
	v_add_f32_e32 v68, v68, v72
	v_mul_f32_e32 v72, v85, v85
	v_mul_f32_e32 v73, v87, v87
	v_fmac_f32_e32 v72, v84, v84
	v_fmac_f32_e32 v73, v86, v86
	v_add_f32_e32 v72, v72, v73
	v_add_f32_e32 v68, v68, v72
	v_mul_f32_e32 v72, v89, v89
	v_mul_f32_e32 v73, v91, v91
	v_fmac_f32_e32 v72, v88, v88
	v_fmac_f32_e32 v73, v90, v90
	v_add_f32_e32 v72, v72, v73
	v_add_f32_e32 v68, v68, v72
	s_waitcnt vmcnt(44)
	v_mul_f32_e32 v69, v93, v93
	v_mul_f32_e32 v73, v95, v95
	v_fmac_f32_e32 v69, v92, v92
	v_fmac_f32_e32 v73, v94, v94
	v_add_f32_e32 v69, v69, v73
	v_mul_f32_e32 v72, v97, v97
	v_mul_f32_e32 v73, v99, v99
	v_fmac_f32_e32 v72, v96, v96
	v_fmac_f32_e32 v73, v98, v98
	v_add_f32_e32 v72, v72, v73
	v_add_f32_e32 v69, v69, v72
	v_mul_f32_e32 v72, v101, v101
	v_mul_f32_e32 v73, v103, v103
	v_fmac_f32_e32 v72, v100, v100
	v_fmac_f32_e32 v73, v102, v102
	v_add_f32_e32 v72, v72, v73
	v_add_f32_e32 v69, v69, v72
	v_mul_f32_e32 v72, v105, v105
	v_mul_f32_e32 v73, v107, v107
	v_fmac_f32_e32 v72, v104, v104
	v_fmac_f32_e32 v73, v106, v106
	v_add_f32_e32 v72, v72, v73
	v_add_f32_e32 v69, v69, v72
	s_waitcnt vmcnt(40)
	v_mul_f32_e32 v70, v109, v109
	v_mul_f32_e32 v73, v111, v111
	v_fmac_f32_e32 v70, v108, v108
	v_fmac_f32_e32 v73, v110, v110
	v_add_f32_e32 v70, v70, v73
	v_mul_f32_e32 v72, v113, v113
	v_mul_f32_e32 v73, v115, v115
	v_fmac_f32_e32 v72, v112, v112
	v_fmac_f32_e32 v73, v114, v114
	v_add_f32_e32 v72, v72, v73
	v_add_f32_e32 v70, v70, v72
	v_mul_f32_e32 v72, v117, v117
	v_mul_f32_e32 v73, v119, v119
	v_fmac_f32_e32 v72, v116, v116
	v_fmac_f32_e32 v73, v118, v118
	v_add_f32_e32 v72, v72, v73
	v_add_f32_e32 v70, v70, v72
	v_mul_f32_e32 v72, v121, v121
	v_mul_f32_e32 v73, v123, v123
	v_fmac_f32_e32 v72, v120, v120
	v_fmac_f32_e32 v73, v122, v122
	v_add_f32_e32 v72, v72, v73
	v_add_f32_e32 v70, v70, v72
	s_waitcnt vmcnt(36)
	v_mul_f32_e32 v71, v125, v125
	v_mul_f32_e32 v73, v127, v127
	v_fmac_f32_e32 v71, v124, v124
	v_fmac_f32_e32 v73, v126, v126
	v_add_f32_e32 v71, v71, v73
	v_mul_f32_e32 v72, v129, v129
	v_mul_f32_e32 v73, v131, v131
	v_fmac_f32_e32 v72, v128, v128
	v_fmac_f32_e32 v73, v130, v130
	v_add_f32_e32 v72, v72, v73
	v_add_f32_e32 v71, v71, v72
	v_mul_f32_e32 v72, v133, v133
	v_mul_f32_e32 v73, v135, v135
	v_fmac_f32_e32 v72, v132, v132
	v_fmac_f32_e32 v73, v134, v134
	v_add_f32_e32 v72, v72, v73
	v_add_f32_e32 v71, v71, v72
	v_mul_f32_e32 v72, v137, v137
	v_mul_f32_e32 v73, v139, v139
	v_fmac_f32_e32 v72, v136, v136
	v_fmac_f32_e32 v73, v138, v138
	v_add_f32_e32 v72, v72, v73
	v_add_f32_e32 v71, v71, v72
	v_add_f32_dpp v68, v68, v68 quad_perm:[1,0,3,2] row_mask:0xf bank_mask:0xf
	v_add_f32_dpp v69, v69, v69 quad_perm:[1,0,3,2] row_mask:0xf bank_mask:0xf
	v_add_f32_dpp v70, v70, v70 quad_perm:[1,0,3,2] row_mask:0xf bank_mask:0xf
	v_add_f32_dpp v71, v71, v71 quad_perm:[1,0,3,2] row_mask:0xf bank_mask:0xf
	v_add_f32_dpp v68, v68, v68 quad_perm:[2,3,0,1] row_mask:0xf bank_mask:0xf
	v_add_f32_dpp v69, v69, v69 quad_perm:[2,3,0,1] row_mask:0xf bank_mask:0xf
	v_add_f32_dpp v70, v70, v70 quad_perm:[2,3,0,1] row_mask:0xf bank_mask:0xf
	v_add_f32_dpp v71, v71, v71 quad_perm:[2,3,0,1] row_mask:0xf bank_mask:0xf
	v_add_f32_dpp v68, v68, v68 row_half_mirror row_mask:0xf bank_mask:0xf
	v_add_f32_dpp v69, v69, v69 row_half_mirror row_mask:0xf bank_mask:0xf
; DI unsigned pk2(float lo, float hi) { f32x2_t v = {lo, hi}; bf16x2_t b = __builtin_convertvector(v, bf16x2_t); return __builtin_bit_cast(unsigned, b); }
; __global__ void __launch_bounds__(512, 2) hybrid_fwd(Args args) {
;     ...
;                 s = wave_sum(s); if (F.lane == 0) SS0[m + q * NGW] = s;
;                 u32x2* o8 = (u32x2*)(XB + (size_t)(m + q * NGW) * DM) + F.lane;
; #pragma unroll
;                 for (int j = 0; j < 4; ++j) { u32x2 w; w.x = pk2(v[q][j].x, v[q][j].y); w.y = pk2(v[q][j].z, v[q][j].w); o8[64 * j] = w; } }
	v_add_f32_dpp v70, v70, v70 row_half_mirror row_mask:0xf bank_mask:0xf
	v_add_f32_dpp v71, v71, v71 row_half_mirror row_mask:0xf bank_mask:0xf
	v_add_f32_dpp v68, v68, v68 row_mirror row_mask:0xf bank_mask:0xf
	v_add_f32_dpp v69, v69, v69 row_mirror row_mask:0xf bank_mask:0xf
	v_add_f32_dpp v70, v70, v70 row_mirror row_mask:0xf bank_mask:0xf
	v_add_f32_dpp v71, v71, v71 row_mirror row_mask:0xf bank_mask:0xf
	v_add_f32_dpp v68, v68, v68 row_bcast:15 row_mask:0xa bank_mask:0xf
	v_add_f32_dpp v69, v69, v69 row_bcast:15 row_mask:0xa bank_mask:0xf
	v_add_f32_dpp v70, v70, v70 row_bcast:15 row_mask:0xa bank_mask:0xf
	v_add_f32_dpp v71, v71, v71 row_bcast:15 row_mask:0xa bank_mask:0xf
	v_add_f32_dpp v68, v68, v68 row_bcast:31 row_mask:0xc bank_mask:0xf
	v_add_f32_dpp v69, v69, v69 row_bcast:31 row_mask:0xc bank_mask:0xf
	v_add_f32_dpp v70, v70, v70 row_bcast:31 row_mask:0xc bank_mask:0xf
	v_add_f32_dpp v71, v71, v71 row_bcast:31 row_mask:0xc bank_mask:0xf
	s_and_saveexec_b64 s[8:9], vcc
	s_mov_b32 s2, s7
	s_ashr_i32 s3, s2, 31
	s_lshl_b64 s[38:39], s[2:3], 2
	s_add_u32 s38, s82, s38
	s_addc_u32 s39, s83, s39
	global_store_dword v65, v68, s[38:39]
	s_add_i32 s2, s2, s88
	s_ashr_i32 s3, s2, 31
	s_lshl_b64 s[38:39], s[2:3], 2
	s_add_u32 s38, s82, s38
	s_addc_u32 s39, s83, s39
	global_store_dword v65, v69, s[38:39]
	s_add_i32 s2, s2, s88
	s_ashr_i32 s3, s2, 31
	s_lshl_b64 s[38:39], s[2:3], 2
	s_add_u32 s38, s82, s38
	s_addc_u32 s39, s83, s39
	global_store_dword v65, v70, s[38:39]
	s_add_i32 s2, s2, s88
	s_ashr_i32 s3, s2, 31
	s_lshl_b64 s[38:39], s[2:3], 2
	s_add_u32 s38, s82, s38
	s_addc_u32 s39, s83, s39
	global_store_dword v65, v71, s[38:39]
	s_or_b64 exec, exec, s[8:9]
	s_mov_b32 s2, s7
	s_ashr_i32 s3, s2, 31
	s_lshl_b64 s[0:1], s[2:3], 11
	v_lshl_add_u64 v[72:73], v[66:67], 0, s[0:1]
	v_cvt_pk_bf16_f32 v76, v76, v77
	v_cvt_pk_bf16_f32 v77, v78, v79
	v_cvt_pk_bf16_f32 v80, v80, v81
	v_cvt_pk_bf16_f32 v81, v82, v83
	v_cvt_pk_bf16_f32 v84, v84, v85
	v_cvt_pk_bf16_f32 v85, v86, v87
	v_cvt_pk_bf16_f32 v88, v88, v89
	v_cvt_pk_bf16_f32 v89, v90, v91
	global_store_dwordx2 v[72:73], v[76:77], off
	global_store_dwordx2 v[72:73], v[80:81], off offset:512
	global_store_dwordx2 v[72:73], v[84:85], off offset:1024
	global_store_dwordx2 v[72:73], v[88:89], off offset:1536
	s_add_i32 s2, s2, s88
	s_ashr_i32 s3, s2, 31
	s_lshl_b64 s[0:1], s[2:3], 11
	v_lshl_add_u64 v[72:73], v[66:67], 0, s[0:1]
	v_cvt_pk_bf16_f32 v92, v92, v93
	v_cvt_pk_bf16_f32 v93, v94, v95
	v_cvt_pk_bf16_f32 v96, v96, v97
	v_cvt_pk_bf16_f32 v97, v98, v99
	v_cvt_pk_bf16_f32 v100, v100, v101
	v_cvt_pk_bf16_f32 v101, v102, v103
	v_cvt_pk_bf16_f32 v104, v104, v105
	v_cvt_pk_bf16_f32 v105, v106, v107
	global_store_dwordx2 v[72:73], v[92:93], off
	global_store_dwordx2 v[72:73], v[96:97], off offset:512
	global_store_dwordx2 v[72:73], v[100:101], off offset:1024
	global_store_dwordx2 v[72:73], v[104:105], off offset:1536
	s_add_i32 s2, s2, s88
	s_ashr_i32 s3, s2, 31
	s_lshl_b64 s[0:1], s[2:3], 11
	v_lshl_add_u64 v[72:73], v[66:67], 0, s[0:1]
	v_cvt_pk_bf16_f32 v108, v108, v109
	v_cvt_pk_bf16_f32 v109, v110, v111
	v_cvt_pk_bf16_f32 v112, v112, v113
	v_cvt_pk_bf16_f32 v113, v114, v115
	v_cvt_pk_bf16_f32 v116, v116, v117
	v_cvt_pk_bf16_f32 v117, v118, v119
	v_cvt_pk_bf16_f32 v120, v120, v121
	v_cvt_pk_bf16_f32 v121, v122, v123
	global_store_dwordx2 v[72:73], v[108:109], off
	global_store_dwordx2 v[72:73], v[112:113], off offset:512
	global_store_dwordx2 v[72:73], v[116:117], off offset:1024
	global_store_dwordx2 v[72:73], v[120:121], off offset:1536
	s_add_i32 s2, s2, s88
	s_ashr_i32 s3, s2, 31
	s_lshl_b64 s[0:1], s[2:3], 11
	v_lshl_add_u64 v[72:73], v[66:67], 0, s[0:1]
	v_cvt_pk_bf16_f32 v124, v124, v125
	v_cvt_pk_bf16_f32 v125, v126, v127
	v_cvt_pk_bf16_f32 v128, v128, v129
	v_cvt_pk_bf16_f32 v129, v130, v131
	v_cvt_pk_bf16_f32 v132, v132, v133
	v_cvt_pk_bf16_f32 v133, v134, v135
	v_cvt_pk_bf16_f32 v136, v136, v137
	v_cvt_pk_bf16_f32 v137, v138, v139
	global_store_dwordx2 v[72:73], v[124:125], off
	global_store_dwordx2 v[72:73], v[128:129], off offset:512
	global_store_dwordx2 v[72:73], v[132:133], off offset:1024
	global_store_dwordx2 v[72:73], v[136:137], off offset:1536
	s_add_i32 s7, s6, s14
	s_cmpk_gt_i32 s7, 0x7fff
	s_cbranch_scc1 .Lp0b_lastA
; __global__ void __launch_bounds__(512, 2) hybrid_fwd(Args args) {
;     ...
;         if (sub & 2) for (int m = gw; m < MTOK; m += 4 * NGW) {
;             f32x4 v[4][4];
; #pragma unroll
;             for (int q = 0; q < 4; ++q) { const f32x4* xr = (const f32x4*)xrow(F, m + q * NGW) + F.lane;
; #pragma unroll
;                 for (int j = 0; j < 4; ++j) v[q][j] = xr[64 * j]; }
; #pragma unroll
;             for (int q = 0; q < 4; ++q) { float s = 0.f;
; #pragma unroll
;                 for (int j = 0; j < 4; ++j) s += (v[q][j].x * v[q][j].x + v[q][j].y * v[q][j].y) + (v[q][j].z * v[q][j].z + v[q][j].w * v[q][j].w);
;                 s = wave_sum(s); if (F.lane == 0) SS0[m + q * NGW] = s;
	s_mov_b32 s2, s7
	s_add_i32 s0, s2, 0xffffc000
	s_ashr_i32 s3, s2, 31
	s_cmpk_lt_i32 s2, 0x4000
	s_cselect_b32 s1, s3, 0
	s_cselect_b32 s0, s2, s0
	s_cselect_b32 s4, s65, s67
	s_cselect_b32 s5, s64, s66
	s_lshl_b64 s[0:1], s[0:1], 12
	s_add_u32 s0, s5, s0
	s_addc_u32 s1, s4, s1
	global_load_dwordx4 v[76:79], v64, s[0:1]
	global_load_dwordx4 v[80:83], v64, s[0:1] offset:1024
	global_load_dwordx4 v[84:87], v64, s[0:1] offset:2048
	global_load_dwordx4 v[88:91], v64, s[0:1] offset:3072
	s_add_i32 s2, s2, s88
	s_add_i32 s0, s2, 0xffffc000
	s_ashr_i32 s3, s2, 31
	s_cmpk_lt_i32 s2, 0x4000
	s_cselect_b32 s1, s3, 0
	s_cselect_b32 s0, s2, s0
	s_cselect_b32 s4, s65, s67
	s_cselect_b32 s5, s64, s66
	s_lshl_b64 s[0:1], s[0:1], 12
	s_add_u32 s0, s5, s0
	s_addc_u32 s1, s4, s1
	global_load_dwordx4 v[92:95], v64, s[0:1]
	global_load_dwordx4 v[96:99], v64, s[0:1] offset:1024
	global_load_dwordx4 v[100:103], v64, s[0:1] offset:2048
	global_load_dwordx4 v[104:107], v64, s[0:1] offset:3072
	s_add_i32 s2, s2, s88
	s_add_i32 s0, s2, 0xffffc000
	s_ashr_i32 s3, s2, 31
	s_cmpk_lt_i32 s2, 0x4000
	s_cselect_b32 s1, s3, 0
	s_cselect_b32 s0, s2, s0
	s_cselect_b32 s4, s65, s67
	s_cselect_b32 s5, s64, s66
	s_lshl_b64 s[0:1], s[0:1], 12
	s_add_u32 s0, s5, s0
	s_addc_u32 s1, s4, s1
	global_load_dwordx4 v[108:111], v64, s[0:1]
	global_load_dwordx4 v[112:115], v64, s[0:1] offset:1024
	global_load_dwordx4 v[116:119], v64, s[0:1] offset:2048
	global_load_dwordx4 v[120:123], v64, s[0:1] offset:3072
	s_add_i32 s2, s2, s88
	s_add_i32 s0, s2, 0xffffc000
	s_ashr_i32 s3, s2, 31
	s_cmpk_lt_i32 s2, 0x4000
	s_cselect_b32 s1, s3, 0
	s_cselect_b32 s0, s2, s0
	s_cselect_b32 s4, s65, s67
	s_cselect_b32 s5, s64, s66
	s_lshl_b64 s[0:1], s[0:1], 12
	s_add_u32 s0, s5, s0
	s_addc_u32 s1, s4, s1
	global_load_dwordx4 v[124:127], v64, s[0:1]
	global_load_dwordx4 v[128:131], v64, s[0:1] offset:1024
	global_load_dwordx4 v[132:135], v64, s[0:1] offset:2048
	global_load_dwordx4 v[136:139], v64, s[0:1] offset:3072
	s_waitcnt vmcnt(48)
	v_mul_f32_e32 v68, v1, v1
	v_mul_f32_e32 v73, v3, v3
	v_fmac_f32_e32 v68, v0, v0
	v_fmac_f32_e32 v73, v2, v2
	v_add_f32_e32 v68, v68, v73
	v_mul_f32_e32 v72, v5, v5
	v_mul_f32_e32 v73, v7, v7
	v_fmac_f32_e32 v72, v4, v4
	v_fmac_f32_e32 v73, v6, v6
	v_add_f32_e32 v72, v72, v73
	v_add_f32_e32 v68, v68, v72
	v_mul_f32_e32 v72, v9, v9
	v_mul_f32_e32 v73, v11, v11
	v_fmac_f32_e32 v72, v8, v8
	v_fmac_f32_e32 v73, v10, v10
	v_add_f32_e32 v72, v72, v73
	v_add_f32_e32 v68, v68, v72
	v_mul_f32_e32 v72, v13, v13
	v_mul_f32_e32 v73, v15, v15
	v_fmac_f32_e32 v72, v12, v12
	v_fmac_f32_e32 v73, v14, v14
	v_add_f32_e32 v72, v72, v73
	v_add_f32_e32 v68, v68, v72
	s_waitcnt vmcnt(44)
	v_mul_f32_e32 v69, v17, v17
	v_mul_f32_e32 v73, v19, v19
	v_fmac_f32_e32 v69, v16, v16
	v_fmac_f32_e32 v73, v18, v18
	v_add_f32_e32 v69, v69, v73
	v_mul_f32_e32 v72, v21, v21
	v_mul_f32_e32 v73, v23, v23
	v_fmac_f32_e32 v72, v20, v20
	v_fmac_f32_e32 v73, v22, v22
	v_add_f32_e32 v72, v72, v73
	v_add_f32_e32 v69, v69, v72
	v_mul_f32_e32 v72, v25, v25
	v_mul_f32_e32 v73, v27, v27
	v_fmac_f32_e32 v72, v24, v24
	v_fmac_f32_e32 v73, v26, v26
	v_add_f32_e32 v72, v72, v73
	v_add_f32_e32 v69, v69, v72
	v_mul_f32_e32 v72, v29, v29
	v_mul_f32_e32 v73, v31, v31
	v_fmac_f32_e32 v72, v28, v28
	v_fmac_f32_e32 v73, v30, v30
	v_add_f32_e32 v72, v72, v73
	v_add_f32_e32 v69, v69, v72
	s_waitcnt vmcnt(40)
	v_mul_f32_e32 v70, v33, v33
	v_mul_f32_e32 v73, v35, v35
	v_fmac_f32_e32 v70, v32, v32
	v_fmac_f32_e32 v73, v34, v34
	v_add_f32_e32 v70, v70, v73
	v_mul_f32_e32 v72, v37, v37
	v_mul_f32_e32 v73, v39, v39
	v_fmac_f32_e32 v72, v36, v36
	v_fmac_f32_e32 v73, v38, v38
	v_add_f32_e32 v72, v72, v73
	v_add_f32_e32 v70, v70, v72
	v_mul_f32_e32 v72, v41, v41
	v_mul_f32_e32 v73, v43, v43
	v_fmac_f32_e32 v72, v40, v40
	v_fmac_f32_e32 v73, v42, v42
	v_add_f32_e32 v72, v72, v73
	v_add_f32_e32 v70, v70, v72
	v_mul_f32_e32 v72, v45, v45
	v_mul_f32_e32 v73, v47, v47
	v_fmac_f32_e32 v72, v44, v44
	v_fmac_f32_e32 v73, v46, v46
	v_add_f32_e32 v72, v72, v73
	v_add_f32_e32 v70, v70, v72
	s_waitcnt vmcnt(36)
	v_mul_f32_e32 v71, v49, v49
	v_mul_f32_e32 v73, v51, v51
	v_fmac_f32_e32 v71, v48, v48
	v_fmac_f32_e32 v73, v50, v50
	v_add_f32_e32 v71, v71, v73
	v_mul_f32_e32 v72, v53, v53
	v_mul_f32_e32 v73, v55, v55
	v_fmac_f32_e32 v72, v52, v52
	v_fmac_f32_e32 v73, v54, v54
	v_add_f32_e32 v72, v72, v73
	v_add_f32_e32 v71, v71, v72
	v_mul_f32_e32 v72, v57, v57
	v_mul_f32_e32 v73, v59, v59
	v_fmac_f32_e32 v72, v56, v56
	v_fmac_f32_e32 v73, v58, v58
	v_add_f32_e32 v72, v72, v73
	v_add_f32_e32 v71, v71, v72
	v_mul_f32_e32 v72, v61, v61
	v_mul_f32_e32 v73, v63, v63
	v_fmac_f32_e32 v72, v60, v60
	v_fmac_f32_e32 v73, v62, v62
	v_add_f32_e32 v72, v72, v73
	v_add_f32_e32 v71, v71, v72
	v_add_f32_dpp v68, v68, v68 quad_perm:[1,0,3,2] row_mask:0xf bank_mask:0xf
	v_add_f32_dpp v69, v69, v69 quad_perm:[1,0,3,2] row_mask:0xf bank_mask:0xf
	v_add_f32_dpp v70, v70, v70 quad_perm:[1,0,3,2] row_mask:0xf bank_mask:0xf
	v_add_f32_dpp v71, v71, v71 quad_perm:[1,0,3,2] row_mask:0xf bank_mask:0xf
	v_add_f32_dpp v68, v68, v68 quad_perm:[2,3,0,1] row_mask:0xf bank_mask:0xf
	v_add_f32_dpp v69, v69, v69 quad_perm:[2,3,0,1] row_mask:0xf bank_mask:0xf
	v_add_f32_dpp v70, v70, v70 quad_perm:[2,3,0,1] row_mask:0xf bank_mask:0xf
	v_add_f32_dpp v71, v71, v71 quad_perm:[2,3,0,1] row_mask:0xf bank_mask:0xf
	v_add_f32_dpp v68, v68, v68 row_half_mirror row_mask:0xf bank_mask:0xf
	v_add_f32_dpp v69, v69, v69 row_half_mirror row_mask:0xf bank_mask:0xf
	v_add_f32_dpp v70, v70, v70 row_half_mirror row_mask:0xf bank_mask:0xf
	v_add_f32_dpp v71, v71, v71 row_half_mirror row_mask:0xf bank_mask:0xf
; DI unsigned pk2(float lo, float hi) { f32x2_t v = {lo, hi}; bf16x2_t b = __builtin_convertvector(v, bf16x2_t); return __builtin_bit_cast(unsigned, b); }
; __global__ void __launch_bounds__(512, 2) hybrid_fwd(Args args) {
;     ...
;                 s = wave_sum(s); if (F.lane == 0) SS0[m + q * NGW] = s;
;                 u32x2* o8 = (u32x2*)(XB + (size_t)(m + q * NGW) * DM) + F.lane;
; #pragma unroll
;                 for (int j = 0; j < 4; ++j) { u32x2 w; w.x = pk2(v[q][j].x, v[q][j].y); w.y = pk2(v[q][j].z, v[q][j].w); o8[64 * j] = w; } }
	v_add_f32_dpp v68, v68, v68 row_mirror row_mask:0xf bank_mask:0xf
	v_add_f32_dpp v69, v69, v69 row_mirror row_mask:0xf bank_mask:0xf
	v_add_f32_dpp v70, v70, v70 row_mirror row_mask:0xf bank_mask:0xf
	v_add_f32_dpp v71, v71, v71 row_mirror row_mask:0xf bank_mask:0xf
	v_add_f32_dpp v68, v68, v68 row_bcast:15 row_mask:0xa bank_mask:0xf
	v_add_f32_dpp v69, v69, v69 row_bcast:15 row_mask:0xa bank_mask:0xf
	v_add_f32_dpp v70, v70, v70 row_bcast:15 row_mask:0xa bank_mask:0xf
	v_add_f32_dpp v71, v71, v71 row_bcast:15 row_mask:0xa bank_mask:0xf
	v_add_f32_dpp v68, v68, v68 row_bcast:31 row_mask:0xc bank_mask:0xf
	v_add_f32_dpp v69, v69, v69 row_bcast:31 row_mask:0xc bank_mask:0xf
	v_add_f32_dpp v70, v70, v70 row_bcast:31 row_mask:0xc bank_mask:0xf
	v_add_f32_dpp v71, v71, v71 row_bcast:31 row_mask:0xc bank_mask:0xf
	s_and_saveexec_b64 s[8:9], vcc
	s_mov_b32 s2, s6
	s_ashr_i32 s3, s2, 31
	s_lshl_b64 s[38:39], s[2:3], 2
	s_add_u32 s38, s82, s38
	s_addc_u32 s39, s83, s39
	global_store_dword v65, v68, s[38:39]
	s_add_i32 s2, s2, s88
	s_ashr_i32 s3, s2, 31
	s_lshl_b64 s[38:39], s[2:3], 2
	s_add_u32 s38, s82, s38
	s_addc_u32 s39, s83, s39
	global_store_dword v65, v69, s[38:39]
	s_add_i32 s2, s2, s88
	s_ashr_i32 s3, s2, 31
	s_lshl_b64 s[38:39], s[2:3], 2
	s_add_u32 s38, s82, s38
	s_addc_u32 s39, s83, s39
	global_store_dword v65, v70, s[38:39]
	s_add_i32 s2, s2, s88
	s_ashr_i32 s3, s2, 31
	s_lshl_b64 s[38:39], s[2:3], 2
	s_add_u32 s38, s82, s38
	s_addc_u32 s39, s83, s39
	global_store_dword v65, v71, s[38:39]
	s_or_b64 exec, exec, s[8:9]
	s_mov_b32 s2, s6
	s_ashr_i32 s3, s2, 31
	s_lshl_b64 s[0:1], s[2:3], 11
	v_lshl_add_u64 v[72:73], v[66:67], 0, s[0:1]
	v_cvt_pk_bf16_f32 v0, v0, v1
	v_cvt_pk_bf16_f32 v1, v2, v3
	v_cvt_pk_bf16_f32 v4, v4, v5
	v_cvt_pk_bf16_f32 v5, v6, v7
	v_cvt_pk_bf16_f32 v8, v8, v9
	v_cvt_pk_bf16_f32 v9, v10, v11
	v_cvt_pk_bf16_f32 v12, v12, v13
	v_cvt_pk_bf16_f32 v13, v14, v15
	global_store_dwordx2 v[72:73], v[0:1], off
	global_store_dwordx2 v[72:73], v[4:5], off offset:512
	global_store_dwordx2 v[72:73], v[8:9], off offset:1024
	global_store_dwordx2 v[72:73], v[12:13], off offset:1536
	s_add_i32 s2, s2, s88
	s_ashr_i32 s3, s2, 31
	s_lshl_b64 s[0:1], s[2:3], 11
	v_lshl_add_u64 v[72:73], v[66:67], 0, s[0:1]
	v_cvt_pk_bf16_f32 v16, v16, v17
	v_cvt_pk_bf16_f32 v17, v18, v19
	v_cvt_pk_bf16_f32 v20, v20, v21
	v_cvt_pk_bf16_f32 v21, v22, v23
	v_cvt_pk_bf16_f32 v24, v24, v25
	v_cvt_pk_bf16_f32 v25, v26, v27
	v_cvt_pk_bf16_f32 v28, v28, v29
	v_cvt_pk_bf16_f32 v29, v30, v31
	global_store_dwordx2 v[72:73], v[16:17], off
	global_store_dwordx2 v[72:73], v[20:21], off offset:512
	global_store_dwordx2 v[72:73], v[24:25], off offset:1024
	global_store_dwordx2 v[72:73], v[28:29], off offset:1536
	s_add_i32 s2, s2, s88
	s_ashr_i32 s3, s2, 31
	s_lshl_b64 s[0:1], s[2:3], 11
	v_lshl_add_u64 v[72:73], v[66:67], 0, s[0:1]
	v_cvt_pk_bf16_f32 v32, v32, v33
	v_cvt_pk_bf16_f32 v33, v34, v35
	v_cvt_pk_bf16_f32 v36, v36, v37
	v_cvt_pk_bf16_f32 v37, v38, v39
	v_cvt_pk_bf16_f32 v40, v40, v41
	v_cvt_pk_bf16_f32 v41, v42, v43
	v_cvt_pk_bf16_f32 v44, v44, v45
	v_cvt_pk_bf16_f32 v45, v46, v47
	global_store_dwordx2 v[72:73], v[32:33], off
	global_store_dwordx2 v[72:73], v[36:37], off offset:512
	global_store_dwordx2 v[72:73], v[40:41], off offset:1024
	global_store_dwordx2 v[72:73], v[44:45], off offset:1536
	s_add_i32 s2, s2, s88
	s_ashr_i32 s3, s2, 31
	s_lshl_b64 s[0:1], s[2:3], 11
	v_lshl_add_u64 v[72:73], v[66:67], 0, s[0:1]
	v_cvt_pk_bf16_f32 v48, v48, v49
	v_cvt_pk_bf16_f32 v49, v50, v51
	v_cvt_pk_bf16_f32 v52, v52, v53
	v_cvt_pk_bf16_f32 v53, v54, v55
	v_cvt_pk_bf16_f32 v56, v56, v57
	v_cvt_pk_bf16_f32 v57, v58, v59
	v_cvt_pk_bf16_f32 v60, v60, v61
	v_cvt_pk_bf16_f32 v61, v62, v63
	global_store_dwordx2 v[72:73], v[48:49], off
	global_store_dwordx2 v[72:73], v[52:53], off offset:512
	global_store_dwordx2 v[72:73], v[56:57], off offset:1024
	global_store_dwordx2 v[72:73], v[60:61], off offset:1536
	s_branch .Lp0b_loop
.Lp0b_only:
	s_waitcnt vmcnt(12)
	v_mul_f32_e32 v68, v1, v1
	v_mul_f32_e32 v73, v3, v3
	v_fmac_f32_e32 v68, v0, v0
	v_fmac_f32_e32 v73, v2, v2
	v_add_f32_e32 v68, v68, v73
	v_mul_f32_e32 v72, v5, v5
	v_mul_f32_e32 v73, v7, v7
	v_fmac_f32_e32 v72, v4, v4
	v_fmac_f32_e32 v73, v6, v6
	v_add_f32_e32 v72, v72, v73
	v_add_f32_e32 v68, v68, v72
	v_mul_f32_e32 v72, v9, v9
	v_mul_f32_e32 v73, v11, v11
	v_fmac_f32_e32 v72, v8, v8
	v_fmac_f32_e32 v73, v10, v10
	v_add_f32_e32 v72, v72, v73
	v_add_f32_e32 v68, v68, v72
	v_mul_f32_e32 v72, v13, v13
	v_mul_f32_e32 v73, v15, v15
	v_fmac_f32_e32 v72, v12, v12
	v_fmac_f32_e32 v73, v14, v14
	v_add_f32_e32 v72, v72, v73
	v_add_f32_e32 v68, v68, v72
	s_waitcnt vmcnt(8)
	v_mul_f32_e32 v69, v17, v17
	v_mul_f32_e32 v73, v19, v19
	v_fmac_f32_e32 v69, v16, v16
	v_fmac_f32_e32 v73, v18, v18
	v_add_f32_e32 v69, v69, v73
	v_mul_f32_e32 v72, v21, v21
	v_mul_f32_e32 v73, v23, v23
	v_fmac_f32_e32 v72, v20, v20
	v_fmac_f32_e32 v73, v22, v22
	v_add_f32_e32 v72, v72, v73
	v_add_f32_e32 v69, v69, v72
	v_mul_f32_e32 v72, v25, v25
	v_mul_f32_e32 v73, v27, v27
	v_fmac_f32_e32 v72, v24, v24
	v_fmac_f32_e32 v73, v26, v26
	v_add_f32_e32 v72, v72, v73
	v_add_f32_e32 v69, v69, v72
	v_mul_f32_e32 v72, v29, v29
	v_mul_f32_e32 v73, v31, v31
	v_fmac_f32_e32 v72, v28, v28
	v_fmac_f32_e32 v73, v30, v30
	v_add_f32_e32 v72, v72, v73
	v_add_f32_e32 v69, v69, v72
	s_waitcnt vmcnt(4)
; DI unsigned pk2(float lo, float hi) { f32x2_t v = {lo, hi}; bf16x2_t b = __builtin_convertvector(v, bf16x2_t); return __builtin_bit_cast(unsigned, b); }
; __global__ void __launch_bounds__(512, 2) hybrid_fwd(Args args) {
;     ...
;             for (int q = 0; q < 4; ++q) { float s = 0.f;
; #pragma unroll
;                 for (int j = 0; j < 4; ++j) s += (v[q][j].x * v[q][j].x + v[q][j].y * v[q][j].y) + (v[q][j].z * v[q][j].z + v[q][j].w * v[q][j].w);
;                 s = wave_sum(s); if (F.lane == 0) SS0[m + q * NGW] = s;
;                 u32x2* o8 = (u32x2*)(XB + (size_t)(m + q * NGW) * DM) + F.lane;
; #pragma unroll
;                 for (int j = 0; j < 4; ++j) { u32x2 w; w.x = pk2(v[q][j].x, v[q][j].y); w.y = pk2(v[q][j].z, v[q][j].w); o8[64 * j] = w; } }
	v_mul_f32_e32 v70, v33, v33
	v_mul_f32_e32 v73, v35, v35
	v_fmac_f32_e32 v70, v32, v32
	v_fmac_f32_e32 v73, v34, v34
	v_add_f32_e32 v70, v70, v73
	v_mul_f32_e32 v72, v37, v37
	v_mul_f32_e32 v73, v39, v39
	v_fmac_f32_e32 v72, v36, v36
	v_fmac_f32_e32 v73, v38, v38
	v_add_f32_e32 v72, v72, v73
	v_add_f32_e32 v70, v70, v72
	v_mul_f32_e32 v72, v41, v41
	v_mul_f32_e32 v73, v43, v43
	v_fmac_f32_e32 v72, v40, v40
	v_fmac_f32_e32 v73, v42, v42
	v_add_f32_e32 v72, v72, v73
	v_add_f32_e32 v70, v70, v72
	v_mul_f32_e32 v72, v45, v45
	v_mul_f32_e32 v73, v47, v47
	v_fmac_f32_e32 v72, v44, v44
	v_fmac_f32_e32 v73, v46, v46
	v_add_f32_e32 v72, v72, v73
	v_add_f32_e32 v70, v70, v72
	s_waitcnt vmcnt(0)
	v_mul_f32_e32 v71, v49, v49
	v_mul_f32_e32 v73, v51, v51
	v_fmac_f32_e32 v71, v48, v48
	v_fmac_f32_e32 v73, v50, v50
	v_add_f32_e32 v71, v71, v73
	v_mul_f32_e32 v72, v53, v53
	v_mul_f32_e32 v73, v55, v55
	v_fmac_f32_e32 v72, v52, v52
	v_fmac_f32_e32 v73, v54, v54
	v_add_f32_e32 v72, v72, v73
	v_add_f32_e32 v71, v71, v72
	v_mul_f32_e32 v72, v57, v57
	v_mul_f32_e32 v73, v59, v59
	v_fmac_f32_e32 v72, v56, v56
	v_fmac_f32_e32 v73, v58, v58
	v_add_f32_e32 v72, v72, v73
	v_add_f32_e32 v71, v71, v72
	v_mul_f32_e32 v72, v61, v61
	v_mul_f32_e32 v73, v63, v63
	v_fmac_f32_e32 v72, v60, v60
	v_fmac_f32_e32 v73, v62, v62
	v_add_f32_e32 v72, v72, v73
	v_add_f32_e32 v71, v71, v72
	v_add_f32_dpp v68, v68, v68 quad_perm:[1,0,3,2] row_mask:0xf bank_mask:0xf
	v_add_f32_dpp v69, v69, v69 quad_perm:[1,0,3,2] row_mask:0xf bank_mask:0xf
	v_add_f32_dpp v70, v70, v70 quad_perm:[1,0,3,2] row_mask:0xf bank_mask:0xf
	v_add_f32_dpp v71, v71, v71 quad_perm:[1,0,3,2] row_mask:0xf bank_mask:0xf
	v_add_f32_dpp v68, v68, v68 quad_perm:[2,3,0,1] row_mask:0xf bank_mask:0xf
	v_add_f32_dpp v69, v69, v69 quad_perm:[2,3,0,1] row_mask:0xf bank_mask:0xf
	v_add_f32_dpp v70, v70, v70 quad_perm:[2,3,0,1] row_mask:0xf bank_mask:0xf
	v_add_f32_dpp v71, v71, v71 quad_perm:[2,3,0,1] row_mask:0xf bank_mask:0xf
	v_add_f32_dpp v68, v68, v68 row_half_mirror row_mask:0xf bank_mask:0xf
	v_add_f32_dpp v69, v69, v69 row_half_mirror row_mask:0xf bank_mask:0xf
	v_add_f32_dpp v70, v70, v70 row_half_mirror row_mask:0xf bank_mask:0xf
	v_add_f32_dpp v71, v71, v71 row_half_mirror row_mask:0xf bank_mask:0xf
	v_add_f32_dpp v68, v68, v68 row_mirror row_mask:0xf bank_mask:0xf
	v_add_f32_dpp v69, v69, v69 row_mirror row_mask:0xf bank_mask:0xf
	v_add_f32_dpp v70, v70, v70 row_mirror row_mask:0xf bank_mask:0xf
	v_add_f32_dpp v71, v71, v71 row_mirror row_mask:0xf bank_mask:0xf
	v_add_f32_dpp v68, v68, v68 row_bcast:15 row_mask:0xa bank_mask:0xf
	v_add_f32_dpp v69, v69, v69 row_bcast:15 row_mask:0xa bank_mask:0xf
	v_add_f32_dpp v70, v70, v70 row_bcast:15 row_mask:0xa bank_mask:0xf
	v_add_f32_dpp v71, v71, v71 row_bcast:15 row_mask:0xa bank_mask:0xf
	v_add_f32_dpp v68, v68, v68 row_bcast:31 row_mask:0xc bank_mask:0xf
	v_add_f32_dpp v69, v69, v69 row_bcast:31 row_mask:0xc bank_mask:0xf
	v_add_f32_dpp v70, v70, v70 row_bcast:31 row_mask:0xc bank_mask:0xf
	v_add_f32_dpp v71, v71, v71 row_bcast:31 row_mask:0xc bank_mask:0xf
	s_and_saveexec_b64 s[8:9], vcc
	s_mov_b32 s2, s6
	s_ashr_i32 s3, s2, 31
	s_lshl_b64 s[38:39], s[2:3], 2
	s_add_u32 s38, s82, s38
	s_addc_u32 s39, s83, s39
	global_store_dword v65, v68, s[38:39]
	s_add_i32 s2, s2, s88
	s_ashr_i32 s3, s2, 31
	s_lshl_b64 s[38:39], s[2:3], 2
	s_add_u32 s38, s82, s38
	s_addc_u32 s39, s83, s39
	global_store_dword v65, v69, s[38:39]
	s_add_i32 s2, s2, s88
	s_ashr_i32 s3, s2, 31
	s_lshl_b64 s[38:39], s[2:3], 2
	s_add_u32 s38, s82, s38
	s_addc_u32 s39, s83, s39
	global_store_dword v65, v70, s[38:39]
	s_add_i32 s2, s2, s88
	s_ashr_i32 s3, s2, 31
	s_lshl_b64 s[38:39], s[2:3], 2
	s_add_u32 s38, s82, s38
	s_addc_u32 s39, s83, s39
	global_store_dword v65, v71, s[38:39]
	s_or_b64 exec, exec, s[8:9]
	s_mov_b32 s2, s6
	s_ashr_i32 s3, s2, 31
	s_lshl_b64 s[0:1], s[2:3], 11
	v_lshl_add_u64 v[72:73], v[66:67], 0, s[0:1]
	v_cvt_pk_bf16_f32 v0, v0, v1
	v_cvt_pk_bf16_f32 v1, v2, v3
	v_cvt_pk_bf16_f32 v4, v4, v5
	v_cvt_pk_bf16_f32 v5, v6, v7
	v_cvt_pk_bf16_f32 v8, v8, v9
	v_cvt_pk_bf16_f32 v9, v10, v11
	v_cvt_pk_bf16_f32 v12, v12, v13
	v_cvt_pk_bf16_f32 v13, v14, v15
	global_store_dwordx2 v[72:73], v[0:1], off
	global_store_dwordx2 v[72:73], v[4:5], off offset:512
	global_store_dwordx2 v[72:73], v[8:9], off offset:1024
	global_store_dwordx2 v[72:73], v[12:13], off offset:1536
	s_add_i32 s2, s2, s88
	s_ashr_i32 s3, s2, 31
	s_lshl_b64 s[0:1], s[2:3], 11
	v_lshl_add_u64 v[72:73], v[66:67], 0, s[0:1]
	v_cvt_pk_bf16_f32 v16, v16, v17
	v_cvt_pk_bf16_f32 v17, v18, v19
	v_cvt_pk_bf16_f32 v20, v20, v21
	v_cvt_pk_bf16_f32 v21, v22, v23
	v_cvt_pk_bf16_f32 v24, v24, v25
	v_cvt_pk_bf16_f32 v25, v26, v27
	v_cvt_pk_bf16_f32 v28, v28, v29
	v_cvt_pk_bf16_f32 v29, v30, v31
	global_store_dwordx2 v[72:73], v[16:17], off
	global_store_dwordx2 v[72:73], v[20:21], off offset:512
	global_store_dwordx2 v[72:73], v[24:25], off offset:1024
	global_store_dwordx2 v[72:73], v[28:29], off offset:1536
	s_add_i32 s2, s2, s88
	s_ashr_i32 s3, s2, 31
	s_lshl_b64 s[0:1], s[2:3], 11
	v_lshl_add_u64 v[72:73], v[66:67], 0, s[0:1]
	v_cvt_pk_bf16_f32 v32, v32, v33
	v_cvt_pk_bf16_f32 v33, v34, v35
	v_cvt_pk_bf16_f32 v36, v36, v37
	v_cvt_pk_bf16_f32 v37, v38, v39
	v_cvt_pk_bf16_f32 v40, v40, v41
	v_cvt_pk_bf16_f32 v41, v42, v43
	v_cvt_pk_bf16_f32 v44, v44, v45
	v_cvt_pk_bf16_f32 v45, v46, v47
	global_store_dwordx2 v[72:73], v[32:33], off
	global_store_dwordx2 v[72:73], v[36:37], off offset:512
	global_store_dwordx2 v[72:73], v[40:41], off offset:1024
	global_store_dwordx2 v[72:73], v[44:45], off offset:1536
	s_add_i32 s2, s2, s88
	s_ashr_i32 s3, s2, 31
	s_lshl_b64 s[0:1], s[2:3], 11
	v_lshl_add_u64 v[72:73], v[66:67], 0, s[0:1]
	v_cvt_pk_bf16_f32 v48, v48, v49
	v_cvt_pk_bf16_f32 v49, v50, v51
	v_cvt_pk_bf16_f32 v52, v52, v53
	v_cvt_pk_bf16_f32 v53, v54, v55
	v_cvt_pk_bf16_f32 v56, v56, v57
	v_cvt_pk_bf16_f32 v57, v58, v59
	v_cvt_pk_bf16_f32 v60, v60, v61
	v_cvt_pk_bf16_f32 v61, v62, v63
	global_store_dwordx2 v[72:73], v[48:49], off
	global_store_dwordx2 v[72:73], v[52:53], off offset:512
	global_store_dwordx2 v[72:73], v[56:57], off offset:1024
	global_store_dwordx2 v[72:73], v[60:61], off offset:1536
	s_branch .LBB0_158
; DI unsigned pk2(float lo, float hi) { f32x2_t v = {lo, hi}; bf16x2_t b = __builtin_convertvector(v, bf16x2_t); return __builtin_bit_cast(unsigned, b); }
; __global__ void __launch_bounds__(512, 2) hybrid_fwd(Args args) {
;     ...
;             for (int q = 0; q < 4; ++q) { float s = 0.f;
; #pragma unroll
;                 for (int j = 0; j < 4; ++j) s += (v[q][j].x * v[q][j].x + v[q][j].y * v[q][j].y) + (v[q][j].z * v[q][j].z + v[q][j].w * v[q][j].w);
;                 s = wave_sum(s); if (F.lane == 0) SS0[m + q * NGW] = s;
;                 u32x2* o8 = (u32x2*)(XB + (size_t)(m + q * NGW) * DM) + F.lane;
; #pragma unroll
;                 for (int j = 0; j < 4; ++j) { u32x2 w; w.x = pk2(v[q][j].x, v[q][j].y); w.y = pk2(v[q][j].z, v[q][j].w); o8[64 * j] = w; } }
.Lp0b_lastA:
	s_waitcnt vmcnt(32)
	v_mul_f32_e32 v68, v1, v1
	v_mul_f32_e32 v73, v3, v3
	v_fmac_f32_e32 v68, v0, v0
	v_fmac_f32_e32 v73, v2, v2
	v_add_f32_e32 v68, v68, v73
	v_mul_f32_e32 v72, v5, v5
	v_mul_f32_e32 v73, v7, v7
	v_fmac_f32_e32 v72, v4, v4
	v_fmac_f32_e32 v73, v6, v6
	v_add_f32_e32 v72, v72, v73
	v_add_f32_e32 v68, v68, v72
	v_mul_f32_e32 v72, v9, v9
	v_mul_f32_e32 v73, v11, v11
	v_fmac_f32_e32 v72, v8, v8
	v_fmac_f32_e32 v73, v10, v10
	v_add_f32_e32 v72, v72, v73
	v_add_f32_e32 v68, v68, v72
	v_mul_f32_e32 v72, v13, v13
	v_mul_f32_e32 v73, v15, v15
	v_fmac_f32_e32 v72, v12, v12
	v_fmac_f32_e32 v73, v14, v14
	v_add_f32_e32 v72, v72, v73
	v_add_f32_e32 v68, v68, v72
	s_waitcnt vmcnt(28)
	v_mul_f32_e32 v69, v17, v17
	v_mul_f32_e32 v73, v19, v19
	v_fmac_f32_e32 v69, v16, v16
	v_fmac_f32_e32 v73, v18, v18
	v_add_f32_e32 v69, v69, v73
	v_mul_f32_e32 v72, v21, v21
	v_mul_f32_e32 v73, v23, v23
	v_fmac_f32_e32 v72, v20, v20
	v_fmac_f32_e32 v73, v22, v22
	v_add_f32_e32 v72, v72, v73
	v_add_f32_e32 v69, v69, v72
	v_mul_f32_e32 v72, v25, v25
	v_mul_f32_e32 v73, v27, v27
	v_fmac_f32_e32 v72, v24, v24
	v_fmac_f32_e32 v73, v26, v26
	v_add_f32_e32 v72, v72, v73
	v_add_f32_e32 v69, v69, v72
	v_mul_f32_e32 v72, v29, v29
	v_mul_f32_e32 v73, v31, v31
	v_fmac_f32_e32 v72, v28, v28
	v_fmac_f32_e32 v73, v30, v30
	v_add_f32_e32 v72, v72, v73
	v_add_f32_e32 v69, v69, v72
	s_waitcnt vmcnt(24)
	v_mul_f32_e32 v70, v33, v33
	v_mul_f32_e32 v73, v35, v35
	v_fmac_f32_e32 v70, v32, v32
	v_fmac_f32_e32 v73, v34, v34
	v_add_f32_e32 v70, v70, v73
	v_mul_f32_e32 v72, v37, v37
	v_mul_f32_e32 v73, v39, v39
	v_fmac_f32_e32 v72, v36, v36
	v_fmac_f32_e32 v73, v38, v38
	v_add_f32_e32 v72, v72, v73
	v_add_f32_e32 v70, v70, v72
	v_mul_f32_e32 v72, v41, v41
	v_mul_f32_e32 v73, v43, v43
	v_fmac_f32_e32 v72, v40, v40
	v_fmac_f32_e32 v73, v42, v42
	v_add_f32_e32 v72, v72, v73
	v_add_f32_e32 v70, v70, v72
	v_mul_f32_e32 v72, v45, v45
	v_mul_f32_e32 v73, v47, v47
	v_fmac_f32_e32 v72, v44, v44
	v_fmac_f32_e32 v73, v46, v46
	v_add_f32_e32 v72, v72, v73
	v_add_f32_e32 v70, v70, v72
	s_waitcnt vmcnt(20)
	v_mul_f32_e32 v71, v49, v49
	v_mul_f32_e32 v73, v51, v51
	v_fmac_f32_e32 v71, v48, v48
	v_fmac_f32_e32 v73, v50, v50
	v_add_f32_e32 v71, v71, v73
	v_mul_f32_e32 v72, v53, v53
	v_mul_f32_e32 v73, v55, v55
	v_fmac_f32_e32 v72, v52, v52
	v_fmac_f32_e32 v73, v54, v54
	v_add_f32_e32 v72, v72, v73
	v_add_f32_e32 v71, v71, v72
	v_mul_f32_e32 v72, v57, v57
	v_mul_f32_e32 v73, v59, v59
	v_fmac_f32_e32 v72, v56, v56
	v_fmac_f32_e32 v73, v58, v58
	v_add_f32_e32 v72, v72, v73
	v_add_f32_e32 v71, v71, v72
	v_mul_f32_e32 v72, v61, v61
	v_mul_f32_e32 v73, v63, v63
	v_fmac_f32_e32 v72, v60, v60
	v_fmac_f32_e32 v73, v62, v62
	v_add_f32_e32 v72, v72, v73
	v_add_f32_e32 v71, v71, v72
	v_add_f32_dpp v68, v68, v68 quad_perm:[1,0,3,2] row_mask:0xf bank_mask:0xf
	v_add_f32_dpp v69, v69, v69 quad_perm:[1,0,3,2] row_mask:0xf bank_mask:0xf
	v_add_f32_dpp v70, v70, v70 quad_perm:[1,0,3,2] row_mask:0xf bank_mask:0xf
	v_add_f32_dpp v71, v71, v71 quad_perm:[1,0,3,2] row_mask:0xf bank_mask:0xf
	v_add_f32_dpp v68, v68, v68 quad_perm:[2,3,0,1] row_mask:0xf bank_mask:0xf
	v_add_f32_dpp v69, v69, v69 quad_perm:[2,3,0,1] row_mask:0xf bank_mask:0xf
	v_add_f32_dpp v70, v70, v70 quad_perm:[2,3,0,1] row_mask:0xf bank_mask:0xf
	v_add_f32_dpp v71, v71, v71 quad_perm:[2,3,0,1] row_mask:0xf bank_mask:0xf
	v_add_f32_dpp v68, v68, v68 row_half_mirror row_mask:0xf bank_mask:0xf
	v_add_f32_dpp v69, v69, v69 row_half_mirror row_mask:0xf bank_mask:0xf
	v_add_f32_dpp v70, v70, v70 row_half_mirror row_mask:0xf bank_mask:0xf
	v_add_f32_dpp v71, v71, v71 row_half_mirror row_mask:0xf bank_mask:0xf
	v_add_f32_dpp v68, v68, v68 row_mirror row_mask:0xf bank_mask:0xf
	v_add_f32_dpp v69, v69, v69 row_mirror row_mask:0xf bank_mask:0xf
	v_add_f32_dpp v70, v70, v70 row_mirror row_mask:0xf bank_mask:0xf
	v_add_f32_dpp v71, v71, v71 row_mirror row_mask:0xf bank_mask:0xf
	v_add_f32_dpp v68, v68, v68 row_bcast:15 row_mask:0xa bank_mask:0xf
	v_add_f32_dpp v69, v69, v69 row_bcast:15 row_mask:0xa bank_mask:0xf
	v_add_f32_dpp v70, v70, v70 row_bcast:15 row_mask:0xa bank_mask:0xf
	v_add_f32_dpp v71, v71, v71 row_bcast:15 row_mask:0xa bank_mask:0xf
	v_add_f32_dpp v68, v68, v68 row_bcast:31 row_mask:0xc bank_mask:0xf
	v_add_f32_dpp v69, v69, v69 row_bcast:31 row_mask:0xc bank_mask:0xf
	v_add_f32_dpp v70, v70, v70 row_bcast:31 row_mask:0xc bank_mask:0xf
	v_add_f32_dpp v71, v71, v71 row_bcast:31 row_mask:0xc bank_mask:0xf
	s_and_saveexec_b64 s[8:9], vcc
	s_mov_b32 s2, s6
	s_ashr_i32 s3, s2, 31
	s_lshl_b64 s[38:39], s[2:3], 2
	s_add_u32 s38, s82, s38
	s_addc_u32 s39, s83, s39
	global_store_dword v65, v68, s[38:39]
	s_add_i32 s2, s2, s88
	s_ashr_i32 s3, s2, 31
	s_lshl_b64 s[38:39], s[2:3], 2
	s_add_u32 s38, s82, s38
	s_addc_u32 s39, s83, s39
	global_store_dword v65, v69, s[38:39]
	s_add_i32 s2, s2, s88
	s_ashr_i32 s3, s2, 31
	s_lshl_b64 s[38:39], s[2:3], 2
	s_add_u32 s38, s82, s38
	s_addc_u32 s39, s83, s39
	global_store_dword v65, v70, s[38:39]
	s_add_i32 s2, s2, s88
	s_ashr_i32 s3, s2, 31
	s_lshl_b64 s[38:39], s[2:3], 2
	s_add_u32 s38, s82, s38
	s_addc_u32 s39, s83, s39
	global_store_dword v65, v71, s[38:39]
	s_or_b64 exec, exec, s[8:9]
	s_mov_b32 s2, s6
	s_ashr_i32 s3, s2, 31
	s_lshl_b64 s[0:1], s[2:3], 11
	v_lshl_add_u64 v[72:73], v[66:67], 0, s[0:1]
	v_cvt_pk_bf16_f32 v0, v0, v1
	v_cvt_pk_bf16_f32 v1, v2, v3
	v_cvt_pk_bf16_f32 v4, v4, v5
	v_cvt_pk_bf16_f32 v5, v6, v7
	v_cvt_pk_bf16_f32 v8, v8, v9
	v_cvt_pk_bf16_f32 v9, v10, v11
	v_cvt_pk_bf16_f32 v12, v12, v13
	v_cvt_pk_bf16_f32 v13, v14, v15
	global_store_dwordx2 v[72:73], v[0:1], off
; DI unsigned pk2(float lo, float hi) { f32x2_t v = {lo, hi}; bf16x2_t b = __builtin_convertvector(v, bf16x2_t); return __builtin_bit_cast(unsigned, b); }
; __global__ void __launch_bounds__(512, 2) hybrid_fwd(Args args) {
;     ...
;             for (int q = 0; q < 4; ++q) { float s = 0.f;
; #pragma unroll
;                 for (int j = 0; j < 4; ++j) s += (v[q][j].x * v[q][j].x + v[q][j].y * v[q][j].y) + (v[q][j].z * v[q][j].z + v[q][j].w * v[q][j].w);
;                 s = wave_sum(s); if (F.lane == 0) SS0[m + q * NGW] = s;
;                 u32x2* o8 = (u32x2*)(XB + (size_t)(m + q * NGW) * DM) + F.lane;
; #pragma unroll
;                 for (int j = 0; j < 4; ++j) { u32x2 w; w.x = pk2(v[q][j].x, v[q][j].y); w.y = pk2(v[q][j].z, v[q][j].w); o8[64 * j] = w; } }
	global_store_dwordx2 v[72:73], v[4:5], off offset:512
	global_store_dwordx2 v[72:73], v[8:9], off offset:1024
	global_store_dwordx2 v[72:73], v[12:13], off offset:1536
	s_add_i32 s2, s2, s88
	s_ashr_i32 s3, s2, 31
	s_lshl_b64 s[0:1], s[2:3], 11
	v_lshl_add_u64 v[72:73], v[66:67], 0, s[0:1]
	v_cvt_pk_bf16_f32 v16, v16, v17
	v_cvt_pk_bf16_f32 v17, v18, v19
	v_cvt_pk_bf16_f32 v20, v20, v21
	v_cvt_pk_bf16_f32 v21, v22, v23
	v_cvt_pk_bf16_f32 v24, v24, v25
	v_cvt_pk_bf16_f32 v25, v26, v27
	v_cvt_pk_bf16_f32 v28, v28, v29
	v_cvt_pk_bf16_f32 v29, v30, v31
	global_store_dwordx2 v[72:73], v[16:17], off
	global_store_dwordx2 v[72:73], v[20:21], off offset:512
	global_store_dwordx2 v[72:73], v[24:25], off offset:1024
	global_store_dwordx2 v[72:73], v[28:29], off offset:1536
	s_add_i32 s2, s2, s88
	s_ashr_i32 s3, s2, 31
	s_lshl_b64 s[0:1], s[2:3], 11
	v_lshl_add_u64 v[72:73], v[66:67], 0, s[0:1]
	v_cvt_pk_bf16_f32 v32, v32, v33
	v_cvt_pk_bf16_f32 v33, v34, v35
	v_cvt_pk_bf16_f32 v36, v36, v37
	v_cvt_pk_bf16_f32 v37, v38, v39
	v_cvt_pk_bf16_f32 v40, v40, v41
	v_cvt_pk_bf16_f32 v41, v42, v43
	v_cvt_pk_bf16_f32 v44, v44, v45
	v_cvt_pk_bf16_f32 v45, v46, v47
	global_store_dwordx2 v[72:73], v[32:33], off
	global_store_dwordx2 v[72:73], v[36:37], off offset:512
	global_store_dwordx2 v[72:73], v[40:41], off offset:1024
	global_store_dwordx2 v[72:73], v[44:45], off offset:1536
	s_add_i32 s2, s2, s88
	s_ashr_i32 s3, s2, 31
	s_lshl_b64 s[0:1], s[2:3], 11
	v_lshl_add_u64 v[72:73], v[66:67], 0, s[0:1]
	v_cvt_pk_bf16_f32 v48, v48, v49
	v_cvt_pk_bf16_f32 v49, v50, v51
	v_cvt_pk_bf16_f32 v52, v52, v53
	v_cvt_pk_bf16_f32 v53, v54, v55
	v_cvt_pk_bf16_f32 v56, v56, v57
	v_cvt_pk_bf16_f32 v57, v58, v59
	v_cvt_pk_bf16_f32 v60, v60, v61
	v_cvt_pk_bf16_f32 v61, v62, v63
	global_store_dwordx2 v[72:73], v[48:49], off
	global_store_dwordx2 v[72:73], v[52:53], off offset:512
	global_store_dwordx2 v[72:73], v[56:57], off offset:1024
	global_store_dwordx2 v[72:73], v[60:61], off offset:1536
	s_branch .LBB0_158
.Lp0b_lastB:
	s_waitcnt vmcnt(32)
	v_mul_f32_e32 v68, v77, v77
	v_mul_f32_e32 v73, v79, v79
	v_fmac_f32_e32 v68, v76, v76
	v_fmac_f32_e32 v73, v78, v78
	v_add_f32_e32 v68, v68, v73
	v_mul_f32_e32 v72, v81, v81
	v_mul_f32_e32 v73, v83, v83
	v_fmac_f32_e32 v72, v80, v80
	v_fmac_f32_e32 v73, v82, v82
	v_add_f32_e32 v72, v72, v73
	v_add_f32_e32 v68, v68, v72
	v_mul_f32_e32 v72, v85, v85
	v_mul_f32_e32 v73, v87, v87
	v_fmac_f32_e32 v72, v84, v84
	v_fmac_f32_e32 v73, v86, v86
	v_add_f32_e32 v72, v72, v73
	v_add_f32_e32 v68, v68, v72
	v_mul_f32_e32 v72, v89, v89
	v_mul_f32_e32 v73, v91, v91
	v_fmac_f32_e32 v72, v88, v88
	v_fmac_f32_e32 v73, v90, v90
	v_add_f32_e32 v72, v72, v73
	v_add_f32_e32 v68, v68, v72
	s_waitcnt vmcnt(28)
	v_mul_f32_e32 v69, v93, v93
	v_mul_f32_e32 v73, v95, v95
	v_fmac_f32_e32 v69, v92, v92
	v_fmac_f32_e32 v73, v94, v94
	v_add_f32_e32 v69, v69, v73
	v_mul_f32_e32 v72, v97, v97
	v_mul_f32_e32 v73, v99, v99
	v_fmac_f32_e32 v72, v96, v96
	v_fmac_f32_e32 v73, v98, v98
	v_add_f32_e32 v72, v72, v73
	v_add_f32_e32 v69, v69, v72
	v_mul_f32_e32 v72, v101, v101
	v_mul_f32_e32 v73, v103, v103
	v_fmac_f32_e32 v72, v100, v100
	v_fmac_f32_e32 v73, v102, v102
	v_add_f32_e32 v72, v72, v73
	v_add_f32_e32 v69, v69, v72
	v_mul_f32_e32 v72, v105, v105
	v_mul_f32_e32 v73, v107, v107
	v_fmac_f32_e32 v72, v104, v104
	v_fmac_f32_e32 v73, v106, v106
	v_add_f32_e32 v72, v72, v73
	v_add_f32_e32 v69, v69, v72
	s_waitcnt vmcnt(24)
	v_mul_f32_e32 v70, v109, v109
	v_mul_f32_e32 v73, v111, v111
	v_fmac_f32_e32 v70, v108, v108
	v_fmac_f32_e32 v73, v110, v110
	v_add_f32_e32 v70, v70, v73
	v_mul_f32_e32 v72, v113, v113
	v_mul_f32_e32 v73, v115, v115
	v_fmac_f32_e32 v72, v112, v112
	v_fmac_f32_e32 v73, v114, v114
	v_add_f32_e32 v72, v72, v73
	v_add_f32_e32 v70, v70, v72
	v_mul_f32_e32 v72, v117, v117
	v_mul_f32_e32 v73, v119, v119
	v_fmac_f32_e32 v72, v116, v116
	v_fmac_f32_e32 v73, v118, v118
	v_add_f32_e32 v72, v72, v73
	v_add_f32_e32 v70, v70, v72
	v_mul_f32_e32 v72, v121, v121
	v_mul_f32_e32 v73, v123, v123
	v_fmac_f32_e32 v72, v120, v120
	v_fmac_f32_e32 v73, v122, v122
	v_add_f32_e32 v72, v72, v73
	v_add_f32_e32 v70, v70, v72
	s_waitcnt vmcnt(20)
; DI unsigned pk2(float lo, float hi) { f32x2_t v = {lo, hi}; bf16x2_t b = __builtin_convertvector(v, bf16x2_t); return __builtin_bit_cast(unsigned, b); }
; __global__ void __launch_bounds__(512, 2) hybrid_fwd(Args args) {
;     ...
;             for (int q = 0; q < 4; ++q) { float s = 0.f;
; #pragma unroll
;                 for (int j = 0; j < 4; ++j) s += (v[q][j].x * v[q][j].x + v[q][j].y * v[q][j].y) + (v[q][j].z * v[q][j].z + v[q][j].w * v[q][j].w);
;                 s = wave_sum(s); if (F.lane == 0) SS0[m + q * NGW] = s;
;                 u32x2* o8 = (u32x2*)(XB + (size_t)(m + q * NGW) * DM) + F.lane;
; #pragma unroll
;                 for (int j = 0; j < 4; ++j) { u32x2 w; w.x = pk2(v[q][j].x, v[q][j].y); w.y = pk2(v[q][j].z, v[q][j].w); o8[64 * j] = w; } }
	v_mul_f32_e32 v71, v125, v125
	v_mul_f32_e32 v73, v127, v127
	v_fmac_f32_e32 v71, v124, v124
	v_fmac_f32_e32 v73, v126, v126
	v_add_f32_e32 v71, v71, v73
	v_mul_f32_e32 v72, v129, v129
	v_mul_f32_e32 v73, v131, v131
	v_fmac_f32_e32 v72, v128, v128
	v_fmac_f32_e32 v73, v130, v130
	v_add_f32_e32 v72, v72, v73
	v_add_f32_e32 v71, v71, v72
	v_mul_f32_e32 v72, v133, v133
	v_mul_f32_e32 v73, v135, v135
	v_fmac_f32_e32 v72, v132, v132
	v_fmac_f32_e32 v73, v134, v134
	v_add_f32_e32 v72, v72, v73
	v_add_f32_e32 v71, v71, v72
	v_mul_f32_e32 v72, v137, v137
	v_mul_f32_e32 v73, v139, v139
	v_fmac_f32_e32 v72, v136, v136
	v_fmac_f32_e32 v73, v138, v138
	v_add_f32_e32 v72, v72, v73
	v_add_f32_e32 v71, v71, v72
	v_add_f32_dpp v68, v68, v68 quad_perm:[1,0,3,2] row_mask:0xf bank_mask:0xf
	v_add_f32_dpp v69, v69, v69 quad_perm:[1,0,3,2] row_mask:0xf bank_mask:0xf
	v_add_f32_dpp v70, v70, v70 quad_perm:[1,0,3,2] row_mask:0xf bank_mask:0xf
	v_add_f32_dpp v71, v71, v71 quad_perm:[1,0,3,2] row_mask:0xf bank_mask:0xf
	v_add_f32_dpp v68, v68, v68 quad_perm:[2,3,0,1] row_mask:0xf bank_mask:0xf
	v_add_f32_dpp v69, v69, v69 quad_perm:[2,3,0,1] row_mask:0xf bank_mask:0xf
	v_add_f32_dpp v70, v70, v70 quad_perm:[2,3,0,1] row_mask:0xf bank_mask:0xf
	v_add_f32_dpp v71, v71, v71 quad_perm:[2,3,0,1] row_mask:0xf bank_mask:0xf
	v_add_f32_dpp v68, v68, v68 row_half_mirror row_mask:0xf bank_mask:0xf
	v_add_f32_dpp v69, v69, v69 row_half_mirror row_mask:0xf bank_mask:0xf
	v_add_f32_dpp v70, v70, v70 row_half_mirror row_mask:0xf bank_mask:0xf
	v_add_f32_dpp v71, v71, v71 row_half_mirror row_mask:0xf bank_mask:0xf
	v_add_f32_dpp v68, v68, v68 row_mirror row_mask:0xf bank_mask:0xf
	v_add_f32_dpp v69, v69, v69 row_mirror row_mask:0xf bank_mask:0xf
	v_add_f32_dpp v70, v70, v70 row_mirror row_mask:0xf bank_mask:0xf
	v_add_f32_dpp v71, v71, v71 row_mirror row_mask:0xf bank_mask:0xf
	v_add_f32_dpp v68, v68, v68 row_bcast:15 row_mask:0xa bank_mask:0xf
	v_add_f32_dpp v69, v69, v69 row_bcast:15 row_mask:0xa bank_mask:0xf
	v_add_f32_dpp v70, v70, v70 row_bcast:15 row_mask:0xa bank_mask:0xf
	v_add_f32_dpp v71, v71, v71 row_bcast:15 row_mask:0xa bank_mask:0xf
	v_add_f32_dpp v68, v68, v68 row_bcast:31 row_mask:0xc bank_mask:0xf
	v_add_f32_dpp v69, v69, v69 row_bcast:31 row_mask:0xc bank_mask:0xf
	v_add_f32_dpp v70, v70, v70 row_bcast:31 row_mask:0xc bank_mask:0xf
	v_add_f32_dpp v71, v71, v71 row_bcast:31 row_mask:0xc bank_mask:0xf
	s_and_saveexec_b64 s[8:9], vcc
	s_mov_b32 s2, s7
	s_ashr_i32 s3, s2, 31
	s_lshl_b64 s[38:39], s[2:3], 2
	s_add_u32 s38, s82, s38
	s_addc_u32 s39, s83, s39
	global_store_dword v65, v68, s[38:39]
	s_add_i32 s2, s2, s88
	s_ashr_i32 s3, s2, 31
	s_lshl_b64 s[38:39], s[2:3], 2
	s_add_u32 s38, s82, s38
	s_addc_u32 s39, s83, s39
	global_store_dword v65, v69, s[38:39]
	s_add_i32 s2, s2, s88
	s_ashr_i32 s3, s2, 31
	s_lshl_b64 s[38:39], s[2:3], 2
	s_add_u32 s38, s82, s38
	s_addc_u32 s39, s83, s39
	global_store_dword v65, v70, s[38:39]
	s_add_i32 s2, s2, s88
	s_ashr_i32 s3, s2, 31
	s_lshl_b64 s[38:39], s[2:3], 2
	s_add_u32 s38, s82, s38
	s_addc_u32 s39, s83, s39
	global_store_dword v65, v71, s[38:39]
	s_or_b64 exec, exec, s[8:9]
	s_mov_b32 s2, s7
	s_ashr_i32 s3, s2, 31
	s_lshl_b64 s[0:1], s[2:3], 11
	v_lshl_add_u64 v[72:73], v[66:67], 0, s[0:1]
	v_cvt_pk_bf16_f32 v76, v76, v77
	v_cvt_pk_bf16_f32 v77, v78, v79
	v_cvt_pk_bf16_f32 v80, v80, v81
	v_cvt_pk_bf16_f32 v81, v82, v83
	v_cvt_pk_bf16_f32 v84, v84, v85
	v_cvt_pk_bf16_f32 v85, v86, v87
	v_cvt_pk_bf16_f32 v88, v88, v89
	v_cvt_pk_bf16_f32 v89, v90, v91
	global_store_dwordx2 v[72:73], v[76:77], off
	global_store_dwordx2 v[72:73], v[80:81], off offset:512
	global_store_dwordx2 v[72:73], v[84:85], off offset:1024
	global_store_dwordx2 v[72:73], v[88:89], off offset:1536
	s_add_i32 s2, s2, s88
	s_ashr_i32 s3, s2, 31
	s_lshl_b64 s[0:1], s[2:3], 11
	v_lshl_add_u64 v[72:73], v[66:67], 0, s[0:1]
	v_cvt_pk_bf16_f32 v92, v92, v93
	v_cvt_pk_bf16_f32 v93, v94, v95
	v_cvt_pk_bf16_f32 v96, v96, v97
	v_cvt_pk_bf16_f32 v97, v98, v99
	v_cvt_pk_bf16_f32 v100, v100, v101
	v_cvt_pk_bf16_f32 v101, v102, v103
	v_cvt_pk_bf16_f32 v104, v104, v105
	v_cvt_pk_bf16_f32 v105, v106, v107
	global_store_dwordx2 v[72:73], v[92:93], off
	global_store_dwordx2 v[72:73], v[96:97], off offset:512
	global_store_dwordx2 v[72:73], v[100:101], off offset:1024
	global_store_dwordx2 v[72:73], v[104:105], off offset:1536
	s_add_i32 s2, s2, s88
	s_ashr_i32 s3, s2, 31
	s_lshl_b64 s[0:1], s[2:3], 11
	v_lshl_add_u64 v[72:73], v[66:67], 0, s[0:1]
	v_cvt_pk_bf16_f32 v108, v108, v109
	v_cvt_pk_bf16_f32 v109, v110, v111
	v_cvt_pk_bf16_f32 v112, v112, v113
	v_cvt_pk_bf16_f32 v113, v114, v115
	v_cvt_pk_bf16_f32 v116, v116, v117
	v_cvt_pk_bf16_f32 v117, v118, v119
	v_cvt_pk_bf16_f32 v120, v120, v121
	v_cvt_pk_bf16_f32 v121, v122, v123
	global_store_dwordx2 v[72:73], v[108:109], off
	global_store_dwordx2 v[72:73], v[112:113], off offset:512
	global_store_dwordx2 v[72:73], v[116:117], off offset:1024
	global_store_dwordx2 v[72:73], v[120:121], off offset:1536
	s_add_i32 s2, s2, s88
	s_ashr_i32 s3, s2, 31
	s_lshl_b64 s[0:1], s[2:3], 11
	v_lshl_add_u64 v[72:73], v[66:67], 0, s[0:1]
	v_cvt_pk_bf16_f32 v124, v124, v125
	v_cvt_pk_bf16_f32 v125, v126, v127
	v_cvt_pk_bf16_f32 v128, v128, v129
	v_cvt_pk_bf16_f32 v129, v130, v131
	v_cvt_pk_bf16_f32 v132, v132, v133
	v_cvt_pk_bf16_f32 v133, v134, v135
	v_cvt_pk_bf16_f32 v136, v136, v137
	v_cvt_pk_bf16_f32 v137, v138, v139
	global_store_dwordx2 v[72:73], v[124:125], off
	global_store_dwordx2 v[72:73], v[128:129], off offset:512
	global_store_dwordx2 v[72:73], v[132:133], off offset:1024
	global_store_dwordx2 v[72:73], v[136:137], off offset:1536
	s_branch .LBB0_158
	s_nop 0
	s_nop 0
	s_nop 0
	s_nop 0
	s_nop 0
	s_nop 0
